# speedup vs baseline: 1.0205x; 1.0205x over previous
; #define G_STAGE(bufoff, gbase, voff) do { _Pragma("unroll") for (int _i = 0; _i < 2; ++_i) \
;     __builtin_amdgcn_global_load_lds((const unsigned*)((const char*)(gbase) + (voff)[_i]), (LAS unsigned*)(lds + (bufoff) + ldsw + _i * 8192), 16, 0, 0); } while (0)
; #define G_LDA(dst, b, h) do { _Pragma("unroll") for (int m = 0; m < 4; ++m) _Pragma("unroll") for (int k = 0; k < 2; ++k) dst[m][k] = *(const LAS bf16x8*)(lds + G_SA(b, h) + aoff + m * 2048 + k * 1024); } while (0)
; #define G_LDB(dst, b, h) do { _Pragma("unroll") for (int n = 0; n < 2; ++n) _Pragma("unroll") for (int k = 0; k < 2; ++k) dst[n][k] = *(const LAS bf16x8*)(lds + G_SB(b, h) + boff + n * 2048 + k * 1024); } while (0)
; #define WAIT_V(n) asm volatile("s_waitcnt vmcnt(" #n ")" ::: "memory")
; #define WAIT_L(n) asm volatile("s_waitcnt lgkmcnt(" #n ")" ::: "memory")
; #define BAR __builtin_amdgcn_s_barrier()
; #define SCHED __builtin_amdgcn_sched_barrier(0)
; template <class Epi>
; __device__ __forceinline__ void gemm_phase(const bf16_t* __restrict__ A, int lda, const bf16_t* __restrict__ Bt, int ldb, int K, int nM, int nN, const Epi& epi, LAS unsigned char* lds, int wv) {
;     ...
;         for (int t = 0; t < nt; t += 2) {
;             const bool last = (t == nt - 2);
;             const char* a1 = cA + (size_t)(t + 1) * kstep;
;             const char* a2 = last ? nA : cA + (size_t)(t + 2) * kstep; const char* b2 = last ? nB : cB + (size_t)(t + 2) * kstep;
;             const char* a3 = a2 + kstep; const char* b3 = b2 + kstep;
;             G_LDB(B0, 0, 0); G_LDB(B1, 0, 1); SCHED; G_LDA(At, 0, 0); G_STAGE(G_SA(1, 1), a1 + hstep, voffA);
;             WAIT_V(8); WAIT_L(0); BAR; G_MMA(0, 0, At, B0); G_MMA(0, 1, At, B1); BAR; SCHED;
;             G_LDA(At, 0, 1); G_STAGE(G_SB(0, 0), b2, voffA); G_STAGE(G_SB(0, 1), b2 + hstep, voffA); G_STAGE(G_SA(0, 0), a2, voffA);
;             WAIT_V(8); WAIT_L(0); BAR; G_MMA(1, 0, At, B0); G_MMA(1, 1, At, B1); BAR; SCHED;
;             G_LDB(B0, 1, 0); G_LDB(B1, 1, 1); SCHED; G_LDA(At, 1, 0); G_STAGE(G_SA(0, 1), a2 + hstep, voffA);
;             WAIT_V(8); WAIT_L(0); BAR; G_MMA(0, 0, At, B0); G_MMA(0, 1, At, B1); BAR; SCHED;
;             G_LDA(At, 1, 1); G_STAGE(G_SB(1, 0), b3, voffA); G_STAGE(G_SB(1, 1), b3 + hstep, voffA); G_STAGE(G_SA(1, 0), a3, voffA);
;             WAIT_V(8); WAIT_L(0); BAR; G_MMA(1, 0, At, B0); G_MMA(1, 1, At, B1); BAR; SCHED;
.LBB0_54:
	s_add_u32 s40, s60, 0x100
	s_addc_u32 s41, s61, 0
	s_add_i32 s30, 0, 0x10000
	s_cmp_eq_u32 vcc_hi, 40
	s_cselect_b32 s69, s57, s41
	s_cselect_b32 s68, s56, s40
	s_cselect_b32 s63, s9, vcc_lo
	s_cselect_b32 s62, s8, s66
	s_add_i32 s46, 0, 0x14000
	v_add_u32_e32 v140, s30, v164
	v_add_u32_e32 v166, s46, v164
	ds_read_b128 v[128:131], v140
	ds_read_b128 v[132:135], v140 offset:1024
	ds_read_b128 v[136:139], v140 offset:2048
	ds_read_b128 v[140:143], v140 offset:3072
	ds_read_b128 v[150:153], v166
	ds_read_b128 v[154:157], v166 offset:1024
	ds_read_b128 v[158:161], v166 offset:2048
	ds_read_b128 v[166:169], v166 offset:3072
	v_lshl_add_u64 v[190:191], s[60:61], 0, v[148:149]
	s_add_i32 m0, s7, 0xc000
	ds_read_b128 v[170:173], v165
	ds_read_b128 v[174:177], v165 offset:1024
	ds_read_b128 v[178:181], v165 offset:2048
	ds_read_b128 v[182:185], v165 offset:3072
	ds_read_b128 v[186:189], v165 offset:4096
	ds_read_b128 v[194:197], v165 offset:5120
	ds_read_b128 v[198:201], v165 offset:6144
	ds_read_b128 v[202:205], v165 offset:7168
	global_load_lds_dwordx4 v[190:191], off
	v_lshl_add_u64 v[190:191], s[60:61], 0, v[146:147]
	s_add_i32 m0, s7, 0xe000
	s_nop 0
	global_load_lds_dwordx4 v[190:191], off
	s_waitcnt vmcnt(8)
	s_waitcnt lgkmcnt(0)
	s_barrier
	s_setprio 1
	s_waitcnt lgkmcnt(0)
	v_mfma_f32_16x16x32_bf16 v[124:127], v[128:131], v[170:173], v[124:127]
	v_mfma_f32_16x16x32_bf16 v[120:123], v[136:139], v[170:173], v[120:123]
	v_mfma_f32_16x16x32_bf16 v[108:111], v[128:131], v[178:181], v[108:111]
	v_mfma_f32_16x16x32_bf16 v[104:107], v[136:139], v[178:181], v[104:107]
	v_mfma_f32_16x16x32_bf16 v[92:95], v[128:131], v[186:189], v[92:95]
	v_mfma_f32_16x16x32_bf16 v[88:91], v[136:139], v[186:189], v[88:91]
	v_mfma_f32_16x16x32_bf16 v[76:79], v[128:131], v[198:201], v[76:79]
	v_mfma_f32_16x16x32_bf16 v[72:75], v[136:139], v[198:201], v[72:75]
	v_mfma_f32_16x16x32_bf16 v[124:127], v[132:135], v[174:177], v[124:127]
	v_mfma_f32_16x16x32_bf16 v[120:123], v[140:143], v[174:177], v[120:123]
	v_mfma_f32_16x16x32_bf16 v[108:111], v[132:135], v[182:185], v[108:111]
	v_mfma_f32_16x16x32_bf16 v[104:107], v[140:143], v[182:185], v[104:107]
	v_mfma_f32_16x16x32_bf16 v[92:95], v[132:135], v[194:197], v[92:95]
	v_mfma_f32_16x16x32_bf16 v[88:91], v[140:143], v[194:197], v[88:91]
	v_mfma_f32_16x16x32_bf16 v[76:79], v[132:135], v[202:205], v[76:79]
	v_mfma_f32_16x16x32_bf16 v[72:75], v[140:143], v[202:205], v[72:75]
	s_setprio 0
	s_setprio 1
	v_mfma_f32_16x16x32_bf16 v[116:119], v[150:153], v[170:173], v[116:119]
	v_mfma_f32_16x16x32_bf16 v[112:115], v[158:161], v[170:173], v[112:115]
	v_mfma_f32_16x16x32_bf16 v[100:103], v[150:153], v[178:181], v[100:103]
	v_mfma_f32_16x16x32_bf16 v[96:99], v[158:161], v[178:181], v[96:99]
	v_mfma_f32_16x16x32_bf16 v[84:87], v[150:153], v[186:189], v[84:87]
	v_mfma_f32_16x16x32_bf16 v[80:83], v[158:161], v[186:189], v[80:83]
	v_mfma_f32_16x16x32_bf16 v[68:71], v[150:153], v[198:201], v[68:71]
	v_mfma_f32_16x16x32_bf16 v[64:67], v[158:161], v[198:201], v[64:67]
	v_mfma_f32_16x16x32_bf16 v[116:119], v[154:157], v[174:177], v[116:119]
	v_mfma_f32_16x16x32_bf16 v[112:115], v[166:169], v[174:177], v[112:115]
	v_mfma_f32_16x16x32_bf16 v[100:103], v[154:157], v[182:185], v[100:103]
	v_mfma_f32_16x16x32_bf16 v[96:99], v[166:169], v[182:185], v[96:99]
	v_mfma_f32_16x16x32_bf16 v[84:87], v[154:157], v[194:197], v[84:87]
	v_mfma_f32_16x16x32_bf16 v[80:83], v[166:169], v[194:197], v[80:83]
	v_mfma_f32_16x16x32_bf16 v[68:71], v[154:157], v[202:205], v[68:71]
	v_mfma_f32_16x16x32_bf16 v[64:67], v[166:169], v[202:205], v[64:67]
	s_setprio 0
	s_barrier
	s_add_i32 s30, s30, s33
	v_lshl_add_u64 v[190:191], s[62:63], 0, v[192:193]
	s_mov_b32 m0, s30
	ds_read_b128 v[170:173], v165 offset:16384
	ds_read_b128 v[174:177], v165 offset:17408
	ds_read_b128 v[178:181], v165 offset:18432
	ds_read_b128 v[182:185], v165 offset:19456
	ds_read_b128 v[186:189], v165 offset:20480
	ds_read_b128 v[194:197], v165 offset:21504
	ds_read_b128 v[198:201], v165 offset:22528
	ds_read_b128 v[202:205], v165 offset:23552
	global_load_lds_dwordx4 v[190:191], off
	s_add_i32 m0, s30, 0x2000
	s_add_u32 s30, s62, 0xb0000
	v_lshl_add_u64 v[206:207], s[62:63], 0, v[144:145]
	s_addc_u32 s31, s63, 0
	s_add_i32 s46, s46, s33
	global_load_lds_dwordx4 v[206:207], off
	v_lshl_add_u64 v[208:209], s[30:31], 0, v[192:193]
	s_mov_b32 m0, s46
	v_lshl_add_u64 v[210:211], s[68:69], 0, v[144:145]
	global_load_lds_dwordx4 v[208:209], off
	v_lshl_add_u64 v[208:209], s[30:31], 0, v[144:145]
	s_add_i32 m0, s46, 0x2000
	s_nop 0
	global_load_lds_dwordx4 v[208:209], off
	v_lshl_add_u64 v[208:209], s[68:69], 0, v[192:193]
	s_mov_b32 m0, s7
	s_nop 0
	global_load_lds_dwordx4 v[208:209], off
	s_mov_b32 m0, s29
	s_nop 0
	global_load_lds_dwordx4 v[210:211], off
	s_waitcnt vmcnt(8)
	s_waitcnt lgkmcnt(0)
	s_barrier
; #define G_STAGE(bufoff, gbase, voff) do { _Pragma("unroll") for (int _i = 0; _i < 2; ++_i) \
;     __builtin_amdgcn_global_load_lds((const unsigned*)((const char*)(gbase) + (voff)[_i]), (LAS unsigned*)(lds + (bufoff) + ldsw + _i * 8192), 16, 0, 0); } while (0)
; #define G_LDA(dst, b, h) do { _Pragma("unroll") for (int m = 0; m < 4; ++m) _Pragma("unroll") for (int k = 0; k < 2; ++k) dst[m][k] = *(const LAS bf16x8*)(lds + G_SA(b, h) + aoff + m * 2048 + k * 1024); } while (0)
; #define G_LDB(dst, b, h) do { _Pragma("unroll") for (int n = 0; n < 2; ++n) _Pragma("unroll") for (int k = 0; k < 2; ++k) dst[n][k] = *(const LAS bf16x8*)(lds + G_SB(b, h) + boff + n * 2048 + k * 1024); } while (0)
; #define G_MMA(ai, bj, At, Bt) do { __builtin_amdgcn_s_setprio(1); _Pragma("unroll") for (int m = 0; m < 4; ++m) _Pragma("unroll") for (int n = 0; n < 2; ++n) _Pragma("unroll") for (int k = 0; k < 2; ++k) \
;     acc[ai][bj][m][n] = __builtin_amdgcn_mfma_f32_16x16x32_bf16(Bt[n][k], At[m][k], acc[ai][bj][m][n], 0, 0, 0); __builtin_amdgcn_s_setprio(0); } while (0)
; #define WAIT_V(n) asm volatile("s_waitcnt vmcnt(" #n ")" ::: "memory")
; #define WAIT_L(n) asm volatile("s_waitcnt lgkmcnt(" #n ")" ::: "memory")
; #define BAR __builtin_amdgcn_s_barrier()
; #define SCHED __builtin_amdgcn_sched_barrier(0)
; template <class Epi>
; __device__ __forceinline__ void gemm_phase(const bf16_t* __restrict__ A, int lda, const bf16_t* __restrict__ Bt, int ldb, int K, int nM, int nN, const Epi& epi, LAS unsigned char* lds, int wv) {
;     ...
;             G_LDB(B0, 0, 0); G_LDB(B1, 0, 1); SCHED; G_LDA(At, 0, 0); G_STAGE(G_SA(1, 1), a1 + hstep, voffA);
;             WAIT_V(8); WAIT_L(0); BAR; G_MMA(0, 0, At, B0); G_MMA(0, 1, At, B1); BAR; SCHED;
;             G_LDA(At, 0, 1); G_STAGE(G_SB(0, 0), b2, voffA); G_STAGE(G_SB(0, 1), b2 + hstep, voffA); G_STAGE(G_SA(0, 0), a2, voffA);
;             WAIT_V(8); WAIT_L(0); BAR; G_MMA(1, 0, At, B0); G_MMA(1, 1, At, B1); BAR; SCHED;
;             G_LDB(B0, 1, 0); G_LDB(B1, 1, 1); SCHED; G_LDA(At, 1, 0); G_STAGE(G_SA(0, 1), a2 + hstep, voffA);
;             WAIT_V(8); WAIT_L(0); BAR; G_MMA(0, 0, At, B0); G_MMA(0, 1, At, B1); BAR; SCHED;
;             G_LDA(At, 1, 1); G_STAGE(G_SB(1, 0), b3, voffA); G_STAGE(G_SB(1, 1), b3 + hstep, voffA); G_STAGE(G_SA(1, 0), a3, voffA);
;             WAIT_V(8); WAIT_L(0); BAR; G_MMA(1, 0, At, B0); G_MMA(1, 1, At, B1); BAR; SCHED;
	s_setprio 1
	s_waitcnt lgkmcnt(0)
	v_mfma_f32_16x16x32_bf16 v[60:63], v[128:131], v[170:173], v[60:63]
	v_mfma_f32_16x16x32_bf16 v[56:59], v[136:139], v[170:173], v[56:59]
	v_mfma_f32_16x16x32_bf16 v[44:47], v[128:131], v[178:181], v[44:47]
	v_mfma_f32_16x16x32_bf16 v[40:43], v[136:139], v[178:181], v[40:43]
	v_mfma_f32_16x16x32_bf16 v[28:31], v[128:131], v[186:189], v[28:31]
	v_mfma_f32_16x16x32_bf16 v[24:27], v[136:139], v[186:189], v[24:27]
	v_mfma_f32_16x16x32_bf16 v[12:15], v[128:131], v[198:201], v[12:15]
	v_mfma_f32_16x16x32_bf16 v[8:11], v[136:139], v[198:201], v[8:11]
	v_mfma_f32_16x16x32_bf16 v[60:63], v[132:135], v[174:177], v[60:63]
	v_mfma_f32_16x16x32_bf16 v[56:59], v[140:143], v[174:177], v[56:59]
	v_mfma_f32_16x16x32_bf16 v[44:47], v[132:135], v[182:185], v[44:47]
	v_mfma_f32_16x16x32_bf16 v[40:43], v[140:143], v[182:185], v[40:43]
	v_mfma_f32_16x16x32_bf16 v[28:31], v[132:135], v[194:197], v[28:31]
	v_mfma_f32_16x16x32_bf16 v[24:27], v[140:143], v[194:197], v[24:27]
	v_mfma_f32_16x16x32_bf16 v[12:15], v[132:135], v[202:205], v[12:15]
	v_mfma_f32_16x16x32_bf16 v[8:11], v[140:143], v[202:205], v[8:11]
	s_setprio 0
	s_setprio 1
	v_mfma_f32_16x16x32_bf16 v[52:55], v[150:153], v[170:173], v[52:55]
	v_mfma_f32_16x16x32_bf16 v[48:51], v[158:161], v[170:173], v[48:51]
	v_mfma_f32_16x16x32_bf16 v[36:39], v[150:153], v[178:181], v[36:39]
	v_mfma_f32_16x16x32_bf16 v[32:35], v[158:161], v[178:181], v[32:35]
	v_mfma_f32_16x16x32_bf16 v[20:23], v[150:153], v[186:189], v[20:23]
	v_mfma_f32_16x16x32_bf16 v[16:19], v[158:161], v[186:189], v[16:19]
	v_mfma_f32_16x16x32_bf16 v[4:7], v[150:153], v[198:201], v[4:7]
	v_mfma_f32_16x16x32_bf16 v[0:3], v[158:161], v[198:201], v[0:3]
	v_mfma_f32_16x16x32_bf16 v[52:55], v[154:157], v[174:177], v[52:55]
	v_mfma_f32_16x16x32_bf16 v[48:51], v[166:169], v[174:177], v[48:51]
	v_mfma_f32_16x16x32_bf16 v[36:39], v[154:157], v[182:185], v[36:39]
	v_mfma_f32_16x16x32_bf16 v[32:35], v[166:169], v[182:185], v[32:35]
	v_mfma_f32_16x16x32_bf16 v[20:23], v[154:157], v[194:197], v[20:23]
	v_mfma_f32_16x16x32_bf16 v[16:19], v[166:169], v[194:197], v[16:19]
	v_mfma_f32_16x16x32_bf16 v[4:7], v[154:157], v[202:205], v[4:7]
	v_mfma_f32_16x16x32_bf16 v[0:3], v[166:169], v[202:205], v[0:3]
	s_setprio 0
	s_barrier
	s_add_i32 s46, 0, 0x18000
	s_add_i32 s47, 0, 0x1c000
	v_add_u32_e32 v140, s46, v164
	v_add_u32_e32 v166, s47, v164
	ds_read_b128 v[128:131], v140
	ds_read_b128 v[132:135], v140 offset:1024
	ds_read_b128 v[136:139], v140 offset:2048
	ds_read_b128 v[140:143], v140 offset:3072
	ds_read_b128 v[150:153], v166
	ds_read_b128 v[154:157], v166 offset:1024
	ds_read_b128 v[158:161], v166 offset:2048
	ds_read_b128 v[166:169], v166 offset:3072
	s_add_u32 s30, s68, 0xb0000
	s_addc_u32 s31, s69, 0
	s_mov_b32 m0, s38
	v_lshl_add_u64 v[212:213], s[30:31], 0, v[192:193]
	ds_read_b128 v[170:173], v165 offset:32768
	ds_read_b128 v[174:177], v165 offset:33792
	ds_read_b128 v[178:181], v165 offset:34816
	ds_read_b128 v[182:185], v165 offset:35840
	ds_read_b128 v[186:189], v165 offset:36864
	ds_read_b128 v[194:197], v165 offset:37888
	ds_read_b128 v[198:201], v165 offset:38912
	ds_read_b128 v[202:205], v165 offset:39936
	global_load_lds_dwordx4 v[212:213], off
	v_lshl_add_u64 v[212:213], s[30:31], 0, v[144:145]
	s_mov_b32 m0, s39
	s_nop 0
	global_load_lds_dwordx4 v[212:213], off
	s_waitcnt vmcnt(8)
	s_waitcnt lgkmcnt(0)
	s_barrier
	s_setprio 1
	s_waitcnt lgkmcnt(0)
	v_mfma_f32_16x16x32_bf16 v[124:127], v[128:131], v[170:173], v[124:127]
	v_mfma_f32_16x16x32_bf16 v[120:123], v[136:139], v[170:173], v[120:123]
	v_mfma_f32_16x16x32_bf16 v[108:111], v[128:131], v[178:181], v[108:111]
	v_mfma_f32_16x16x32_bf16 v[104:107], v[136:139], v[178:181], v[104:107]
	v_mfma_f32_16x16x32_bf16 v[92:95], v[128:131], v[186:189], v[92:95]
	v_mfma_f32_16x16x32_bf16 v[88:91], v[136:139], v[186:189], v[88:91]
	v_mfma_f32_16x16x32_bf16 v[76:79], v[128:131], v[198:201], v[76:79]
	v_mfma_f32_16x16x32_bf16 v[72:75], v[136:139], v[198:201], v[72:75]
	v_mfma_f32_16x16x32_bf16 v[124:127], v[132:135], v[174:177], v[124:127]
	v_mfma_f32_16x16x32_bf16 v[120:123], v[140:143], v[174:177], v[120:123]
	v_mfma_f32_16x16x32_bf16 v[108:111], v[132:135], v[182:185], v[108:111]
	v_mfma_f32_16x16x32_bf16 v[104:107], v[140:143], v[182:185], v[104:107]
	v_mfma_f32_16x16x32_bf16 v[92:95], v[132:135], v[194:197], v[92:95]
	v_mfma_f32_16x16x32_bf16 v[88:91], v[140:143], v[194:197], v[88:91]
	v_mfma_f32_16x16x32_bf16 v[76:79], v[132:135], v[202:205], v[76:79]
	v_mfma_f32_16x16x32_bf16 v[72:75], v[140:143], v[202:205], v[72:75]
	s_setprio 0
	s_setprio 1
	v_mfma_f32_16x16x32_bf16 v[116:119], v[150:153], v[170:173], v[116:119]
	v_mfma_f32_16x16x32_bf16 v[112:115], v[158:161], v[170:173], v[112:115]
	v_mfma_f32_16x16x32_bf16 v[100:103], v[150:153], v[178:181], v[100:103]
	v_mfma_f32_16x16x32_bf16 v[96:99], v[158:161], v[178:181], v[96:99]
	v_mfma_f32_16x16x32_bf16 v[84:87], v[150:153], v[186:189], v[84:87]
	v_mfma_f32_16x16x32_bf16 v[80:83], v[158:161], v[186:189], v[80:83]
	v_mfma_f32_16x16x32_bf16 v[68:71], v[150:153], v[198:201], v[68:71]
	v_mfma_f32_16x16x32_bf16 v[64:67], v[158:161], v[198:201], v[64:67]
	v_mfma_f32_16x16x32_bf16 v[116:119], v[154:157], v[174:177], v[116:119]
	v_mfma_f32_16x16x32_bf16 v[112:115], v[166:169], v[174:177], v[112:115]
	v_mfma_f32_16x16x32_bf16 v[100:103], v[154:157], v[182:185], v[100:103]
	v_mfma_f32_16x16x32_bf16 v[96:99], v[166:169], v[182:185], v[96:99]
	v_mfma_f32_16x16x32_bf16 v[84:87], v[154:157], v[194:197], v[84:87]
	v_mfma_f32_16x16x32_bf16 v[80:83], v[166:169], v[194:197], v[80:83]
	v_mfma_f32_16x16x32_bf16 v[68:71], v[154:157], v[202:205], v[68:71]
	v_mfma_f32_16x16x32_bf16 v[64:67], v[166:169], v[202:205], v[64:67]
	s_setprio 0
	s_barrier
; #define WAIT_V(n) asm volatile("s_waitcnt vmcnt(" #n ")" ::: "memory")
; template <class Epi>
; __device__ __forceinline__ void gemm_phase(const bf16_t* __restrict__ A, int lda, const bf16_t* __restrict__ Bt, int ldb, int K, int nM, int nN, const Epi& epi, LAS unsigned char* lds, int wv) {
;     ...
;             WAIT_V(8); WAIT_L(0); BAR; G_MMA(1, 0, At, B0); G_MMA(1, 1, At, B1); BAR; SCHED;
;             G_LDB(B0, 1, 0); G_LDB(B1, 1, 1); SCHED; G_LDA(At, 1, 0); G_STAGE(G_SA(0, 1), a2 + hstep, voffA);
;             WAIT_V(8); WAIT_L(0); BAR; G_MMA(0, 0, At, B0); G_MMA(0, 1, At, B1); BAR; SCHED;
;             G_LDA(At, 1, 1); G_STAGE(G_SB(1, 0), b3, voffA); G_STAGE(G_SB(1, 1), b3 + hstep, voffA); G_STAGE(G_SA(1, 0), a3, voffA);
;             WAIT_V(8); WAIT_L(0); BAR; G_MMA(1, 0, At, B0); G_MMA(1, 1, At, B1); BAR; SCHED;
;         }
;         { int efr = fr, efq = fq; asm volatile("" : "+v"(efr), "+v"(efq));
;           epi(acc, pm, pn, wr, wc, efr, efq); }
;     __device__ __forceinline__ void operator()(AccRef acc, int pm, int pn, int wr, int wc, int fr, int fq) const {
;     ...
;             for (int m = 0; m < 4; ++m) { const int row = EPI_ROW(ai, m); const float* gp = gate + (size_t)(row >> 12) * 9216; const size_t ro = (size_t)row * 1024;
; #pragma unroll
;                 for (int bj = 0; bj < 2; ++bj) { const int col = pn * 256 + wc * 64 + bj * 32 + 8 * fq;
;                     const f32x4 g0 = *(const f32x4*)(gp + col), g1 = *(const f32x4*)(gp + col + 4);
;                     f32x4 x0, x1;
;                     if (mode == 0) { x0 = *(const f32x4*)(xin_f + ro + col); x1 = *(const f32x4*)(xin_f + ro + col + 4); }
;                     else { const h16x8 h = *(const h16x8*)(xh + ro + col); x0 = (f32x4){(float)h[0], (float)h[1], (float)h[2], (float)h[3]}; x1 = (f32x4){(float)h[4], (float)h[5], (float)h[6], (float)h[7]}; }
;                     const f32x4 y0 = x0 + gs * g0 * acc[ai][bj][m][0], y1 = x1 + gs * g1 * acc[ai][bj][m][1];
;                     if (mode == 2) { *(f32x4*)(xout_f + ro + col) = y0; *(f32x4*)(xout_f + ro + col + 4) = y1; }
;                     else { h16x8 h; h[0] = (_Float16)y0[0]; h[1] = (_Float16)y0[1]; h[2] = (_Float16)y0[2]; h[3] = (_Float16)y0[3]; h[4] = (_Float16)y1[0]; h[5] = (_Float16)y1[1]; h[6] = (_Float16)y1[2]; h[7] = (_Float16)y1[3];
;                         *(h16x8*)(xh + ro + col) = h; } } }
	s_add_i32 s30, s46, s33
	v_lshl_add_u64 v[190:191], v[190:191], 0, s[10:11]
	s_mov_b32 m0, s30
	ds_read_b128 v[170:173], v165 offset:49152
	ds_read_b128 v[174:177], v165 offset:50176
	ds_read_b128 v[178:181], v165 offset:51200
	ds_read_b128 v[182:185], v165 offset:52224
	ds_read_b128 v[186:189], v165 offset:53248
	ds_read_b128 v[194:197], v165 offset:54272
	ds_read_b128 v[198:201], v165 offset:55296
	ds_read_b128 v[202:205], v165 offset:56320
	global_load_lds_dwordx4 v[190:191], off
	s_add_i32 m0, s30, 0x2000
	s_add_u32 s30, s62, 0xb0080
	v_lshl_add_u64 v[190:191], v[206:207], 0, s[10:11]
	s_addc_u32 s31, s63, 0
	s_add_i32 s46, s47, s33
	global_load_lds_dwordx4 v[190:191], off
	v_lshl_add_u64 v[190:191], s[30:31], 0, v[192:193]
	s_mov_b32 m0, s46
	s_nop 0
	global_load_lds_dwordx4 v[190:191], off
	v_lshl_add_u64 v[190:191], s[30:31], 0, v[144:145]
	s_add_i32 m0, s46, 0x2000
	s_nop 0
	global_load_lds_dwordx4 v[190:191], off
	v_lshl_add_u64 v[190:191], v[208:209], 0, s[10:11]
	s_mov_b32 m0, s71
	s_nop 0
	global_load_lds_dwordx4 v[190:191], off
	v_lshl_add_u64 v[190:191], v[210:211], 0, s[10:11]
	s_mov_b32 m0, s72
	s_nop 0
	global_load_lds_dwordx4 v[190:191], off
	s_waitcnt vmcnt(8)
	s_waitcnt lgkmcnt(0)
	s_barrier
	s_setprio 1
	s_waitcnt lgkmcnt(0)
	v_mfma_f32_16x16x32_bf16 v[60:63], v[128:131], v[170:173], v[60:63]
	v_mfma_f32_16x16x32_bf16 v[56:59], v[136:139], v[170:173], v[56:59]
	v_mfma_f32_16x16x32_bf16 v[44:47], v[128:131], v[178:181], v[44:47]
	v_mfma_f32_16x16x32_bf16 v[40:43], v[136:139], v[178:181], v[40:43]
	v_mfma_f32_16x16x32_bf16 v[28:31], v[128:131], v[186:189], v[28:31]
	v_mfma_f32_16x16x32_bf16 v[24:27], v[136:139], v[186:189], v[24:27]
	v_mfma_f32_16x16x32_bf16 v[12:15], v[128:131], v[198:201], v[12:15]
	v_mfma_f32_16x16x32_bf16 v[8:11], v[136:139], v[198:201], v[8:11]
	v_mfma_f32_16x16x32_bf16 v[60:63], v[132:135], v[174:177], v[60:63]
	v_mfma_f32_16x16x32_bf16 v[56:59], v[140:143], v[174:177], v[56:59]
	v_mfma_f32_16x16x32_bf16 v[44:47], v[132:135], v[182:185], v[44:47]
	v_mfma_f32_16x16x32_bf16 v[40:43], v[140:143], v[182:185], v[40:43]
	v_mfma_f32_16x16x32_bf16 v[28:31], v[132:135], v[194:197], v[28:31]
	v_mfma_f32_16x16x32_bf16 v[24:27], v[140:143], v[194:197], v[24:27]
	v_mfma_f32_16x16x32_bf16 v[12:15], v[132:135], v[202:205], v[12:15]
	v_mfma_f32_16x16x32_bf16 v[8:11], v[140:143], v[202:205], v[8:11]
	s_setprio 0
	s_setprio 1
	v_mfma_f32_16x16x32_bf16 v[52:55], v[150:153], v[170:173], v[52:55]
	v_mfma_f32_16x16x32_bf16 v[48:51], v[158:161], v[170:173], v[48:51]
	v_mfma_f32_16x16x32_bf16 v[36:39], v[150:153], v[178:181], v[36:39]
	v_mfma_f32_16x16x32_bf16 v[32:35], v[158:161], v[178:181], v[32:35]
	v_mfma_f32_16x16x32_bf16 v[20:23], v[150:153], v[186:189], v[20:23]
	v_mfma_f32_16x16x32_bf16 v[16:19], v[158:161], v[186:189], v[16:19]
	v_mfma_f32_16x16x32_bf16 v[4:7], v[150:153], v[198:201], v[4:7]
	v_mfma_f32_16x16x32_bf16 v[0:3], v[158:161], v[198:201], v[0:3]
	v_mfma_f32_16x16x32_bf16 v[52:55], v[154:157], v[174:177], v[52:55]
	v_mfma_f32_16x16x32_bf16 v[48:51], v[166:169], v[174:177], v[48:51]
	v_mfma_f32_16x16x32_bf16 v[36:39], v[154:157], v[182:185], v[36:39]
	v_mfma_f32_16x16x32_bf16 v[32:35], v[166:169], v[182:185], v[32:35]
	v_mfma_f32_16x16x32_bf16 v[20:23], v[154:157], v[194:197], v[20:23]
	v_mfma_f32_16x16x32_bf16 v[16:19], v[166:169], v[194:197], v[16:19]
	v_mfma_f32_16x16x32_bf16 v[4:7], v[154:157], v[202:205], v[4:7]
	v_mfma_f32_16x16x32_bf16 v[0:3], v[166:169], v[202:205], v[0:3]
	s_setprio 0
	s_barrier
	s_add_i32 vcc_hi, vcc_hi, 2
	s_add_u32 s66, s66, 0x100
	s_addc_u32 vcc_lo, vcc_lo, 0
	s_cmp_gt_u32 vcc_hi, 41
	s_mov_b64 s[60:61], s[40:41]
	s_cbranch_scc0 .LBB0_54
	s_lshl_b32 s8, s94, 8
	v_readlane_b32 s9, v253, 5
	v_mov_b32_e32 v128, v163
	v_mov_b32_e32 v129, v162
	s_add_i32 s8, s8, s9
	v_readlane_b32 s9, v253, 19
	v_add_u32_e32 v152, s8, v129
	s_lshl_b32 s8, s95, 8
	s_or_b32 s8, s8, s9
	v_lshl_add_u32 v150, v128, 3, s8
	s_andn2_b64 vcc, exec, s[52:53]
	s_cbranch_vccnz .Lepi_ffo_slow
	s_and_b64 vcc, exec, s[36:37]
	s_cbranch_vccnz .Lepi_ffo_slow
	v_ashrrev_i32_e32 v154, 12, v152
	v_mul_hi_i32_i24_e32 v155, 0x9000, v154
	v_mul_i32_i24_e32 v154, 0x9000, v154
	v_lshl_add_u64 v[154:155], s[50:51], 0, v[154:155]
	v_ashrrev_i32_e32 v151, 31, v150
	v_lshl_add_u64 v[158:159], v[150:151], 2, v[154:155]
	global_load_dwordx4 v[128:131], v[158:159], off
	global_load_dwordx4 v[132:135], v[158:159], off offset:16
	global_load_dwordx4 v[136:139], v[158:159], off offset:128
	global_load_dwordx4 v[140:143], v[158:159], off offset:144
	v_lshlrev_b32_e32 v153, 11, v152
	v_lshl_add_u32 v153, v150, 1, v153
	s_movk_i32 s66, 0x3ff
	global_load_dwordx4 v[166:169], v153, s[26:27]
	global_load_dwordx4 v[170:173], v153, s[26:27] offset:64
	v_add_u32_e32 v154, 0x8000, v153
	global_load_dwordx4 v[174:177], v154, s[26:27]
	v_add_u32_e32 v154, 0x8000, v153
	global_load_dwordx4 v[178:181], v154, s[26:27] offset:64
	v_add_u32_e32 v154, 0x10000, v153
	global_load_dwordx4 v[182:185], v154, s[26:27]
	v_add_u32_e32 v154, 0x10000, v153
	global_load_dwordx4 v[186:189], v154, s[26:27] offset:64
	v_add_u32_e32 v154, 0x18000, v153
	global_load_dwordx4 v[194:197], v154, s[26:27]
	v_add_u32_e32 v154, 0x18000, v153
	global_load_dwordx4 v[198:201], v154, s[26:27] offset:64
	s_waitcnt vmcnt(8)
	v_pk_mul_f32 v[128:129], v[128:129], 0.5 op_sel_hi:[1,0]
	v_pk_mul_f32 v[130:131], v[130:131], 0.5 op_sel_hi:[1,0]
	v_pk_mul_f32 v[132:133], v[132:133], 0.5 op_sel_hi:[1,0]
	v_pk_mul_f32 v[134:135], v[134:135], 0.5 op_sel_hi:[1,0]
	v_pk_mul_f32 v[136:137], v[136:137], 0.5 op_sel_hi:[1,0]
	v_pk_mul_f32 v[138:139], v[138:139], 0.5 op_sel_hi:[1,0]
	v_pk_mul_f32 v[140:141], v[140:141], 0.5 op_sel_hi:[1,0]
	v_pk_mul_f32 v[142:143], v[142:143], 0.5 op_sel_hi:[1,0]
	s_waitcnt vmcnt(7)
;     __device__ __forceinline__ void operator()(AccRef acc, int pm, int pn, int wr, int wc, int fr, int fq) const {
;     ...
;             for (int m = 0; m < 4; ++m) { const int row = EPI_ROW(ai, m); const float* gp = gate + (size_t)(row >> 12) * 9216; const size_t ro = (size_t)row * 1024;
; #pragma unroll
;                 for (int bj = 0; bj < 2; ++bj) { const int col = pn * 256 + wc * 64 + bj * 32 + 8 * fq;
;                     const f32x4 g0 = *(const f32x4*)(gp + col), g1 = *(const f32x4*)(gp + col + 4);
;                     f32x4 x0, x1;
;                     if (mode == 0) { x0 = *(const f32x4*)(xin_f + ro + col); x1 = *(const f32x4*)(xin_f + ro + col + 4); }
;                     else { const h16x8 h = *(const h16x8*)(xh + ro + col); x0 = (f32x4){(float)h[0], (float)h[1], (float)h[2], (float)h[3]}; x1 = (f32x4){(float)h[4], (float)h[5], (float)h[6], (float)h[7]}; }
;                     const f32x4 y0 = x0 + gs * g0 * acc[ai][bj][m][0], y1 = x1 + gs * g1 * acc[ai][bj][m][1];
;                     if (mode == 2) { *(f32x4*)(xout_f + ro + col) = y0; *(f32x4*)(xout_f + ro + col + 4) = y1; }
;                     else { h16x8 h; h[0] = (_Float16)y0[0]; h[1] = (_Float16)y0[1]; h[2] = (_Float16)y0[2]; h[3] = (_Float16)y0[3]; h[4] = (_Float16)y1[0]; h[5] = (_Float16)y1[1]; h[6] = (_Float16)y1[2]; h[7] = (_Float16)y1[3];
;                         *(h16x8*)(xh + ro + col) = h; } } }
	v_cvt_f32_f16_e32 v202, v166
	v_cvt_f32_f16_sdwa v203, v166 dst_sel:DWORD dst_unused:UNUSED_PAD src0_sel:WORD_1
	v_cvt_f32_f16_e32 v204, v167
	v_cvt_f32_f16_sdwa v205, v167 dst_sel:DWORD dst_unused:UNUSED_PAD src0_sel:WORD_1
	v_cvt_f32_f16_e32 v206, v168
	v_cvt_f32_f16_sdwa v207, v168 dst_sel:DWORD dst_unused:UNUSED_PAD src0_sel:WORD_1
	v_cvt_f32_f16_e32 v208, v169
	v_cvt_f32_f16_sdwa v209, v169 dst_sel:DWORD dst_unused:UNUSED_PAD src0_sel:WORD_1
	v_pk_fma_f32 v[126:127], v[126:127], v[130:131], v[204:205]
	v_pk_fma_f32 v[124:125], v[124:125], v[128:129], v[202:203]
	v_pk_fma_f32 v[122:123], v[122:123], v[134:135], v[208:209]
	v_pk_fma_f32 v[120:121], v[120:121], v[132:133], v[206:207]
	v_cvt_pk_f16_f32 v169, v122, v123
	v_cvt_pk_f16_f32 v168, v120, v121
	v_cvt_pk_f16_f32 v167, v126, v127
	v_cvt_pk_f16_f32 v166, v124, v125
	global_store_dwordx4 v153, v[166:169], s[26:27]
	s_nop 1
	v_add_u32_e32 v154, 0x40000, v153
	global_load_dwordx4 v[166:169], v154, s[26:27]
	s_waitcnt vmcnt(8)
	v_cvt_f32_f16_e32 v202, v170
	v_cvt_f32_f16_sdwa v203, v170 dst_sel:DWORD dst_unused:UNUSED_PAD src0_sel:WORD_1
	v_cvt_f32_f16_e32 v204, v171
	v_cvt_f32_f16_sdwa v205, v171 dst_sel:DWORD dst_unused:UNUSED_PAD src0_sel:WORD_1
	v_cvt_f32_f16_e32 v206, v172
	v_cvt_f32_f16_sdwa v207, v172 dst_sel:DWORD dst_unused:UNUSED_PAD src0_sel:WORD_1
	v_cvt_f32_f16_e32 v208, v173
	v_cvt_f32_f16_sdwa v209, v173 dst_sel:DWORD dst_unused:UNUSED_PAD src0_sel:WORD_1
	v_pk_fma_f32 v[118:119], v[118:119], v[138:139], v[204:205]
	v_pk_fma_f32 v[116:117], v[116:117], v[136:137], v[202:203]
	v_pk_fma_f32 v[114:115], v[114:115], v[142:143], v[208:209]
	v_pk_fma_f32 v[112:113], v[112:113], v[140:141], v[206:207]
	v_cvt_pk_f16_f32 v173, v114, v115
	v_cvt_pk_f16_f32 v172, v112, v113
	v_cvt_pk_f16_f32 v171, v118, v119
	v_cvt_pk_f16_f32 v170, v116, v117
	global_store_dwordx4 v153, v[170:173], s[26:27] offset:64
	s_nop 1
	v_add_u32_e32 v154, 0x40000, v153
	global_load_dwordx4 v[170:173], v154, s[26:27] offset:64
	s_waitcnt vmcnt(9)
	v_cvt_f32_f16_e32 v202, v174
	v_cvt_f32_f16_sdwa v203, v174 dst_sel:DWORD dst_unused:UNUSED_PAD src0_sel:WORD_1
	v_cvt_f32_f16_e32 v204, v175
	v_cvt_f32_f16_sdwa v205, v175 dst_sel:DWORD dst_unused:UNUSED_PAD src0_sel:WORD_1
	v_cvt_f32_f16_e32 v206, v176
	v_cvt_f32_f16_sdwa v207, v176 dst_sel:DWORD dst_unused:UNUSED_PAD src0_sel:WORD_1
	v_cvt_f32_f16_e32 v208, v177
	v_cvt_f32_f16_sdwa v209, v177 dst_sel:DWORD dst_unused:UNUSED_PAD src0_sel:WORD_1
	v_pk_fma_f32 v[110:111], v[110:111], v[130:131], v[204:205]
	v_pk_fma_f32 v[108:109], v[108:109], v[128:129], v[202:203]
	v_pk_fma_f32 v[106:107], v[106:107], v[134:135], v[208:209]
	v_pk_fma_f32 v[104:105], v[104:105], v[132:133], v[206:207]
	v_cvt_pk_f16_f32 v177, v106, v107
	v_cvt_pk_f16_f32 v176, v104, v105
	v_cvt_pk_f16_f32 v175, v110, v111
	v_cvt_pk_f16_f32 v174, v108, v109
	v_add_u32_e32 v155, 0x8000, v153
	global_store_dwordx4 v155, v[174:177], s[26:27]
	s_nop 1
	v_add_u32_e32 v154, 0x48000, v153
	global_load_dwordx4 v[174:177], v154, s[26:27]
	s_waitcnt vmcnt(10)
	v_cvt_f32_f16_e32 v202, v178
	v_cvt_f32_f16_sdwa v203, v178 dst_sel:DWORD dst_unused:UNUSED_PAD src0_sel:WORD_1
	v_cvt_f32_f16_e32 v204, v179
	v_cvt_f32_f16_sdwa v205, v179 dst_sel:DWORD dst_unused:UNUSED_PAD src0_sel:WORD_1
	v_cvt_f32_f16_e32 v206, v180
	v_cvt_f32_f16_sdwa v207, v180 dst_sel:DWORD dst_unused:UNUSED_PAD src0_sel:WORD_1
	v_cvt_f32_f16_e32 v208, v181
	v_cvt_f32_f16_sdwa v209, v181 dst_sel:DWORD dst_unused:UNUSED_PAD src0_sel:WORD_1
	v_pk_fma_f32 v[102:103], v[102:103], v[138:139], v[204:205]
	v_pk_fma_f32 v[100:101], v[100:101], v[136:137], v[202:203]
	v_pk_fma_f32 v[98:99], v[98:99], v[142:143], v[208:209]
	v_pk_fma_f32 v[96:97], v[96:97], v[140:141], v[206:207]
	v_cvt_pk_f16_f32 v181, v98, v99
	v_cvt_pk_f16_f32 v180, v96, v97
	v_cvt_pk_f16_f32 v179, v102, v103
	v_cvt_pk_f16_f32 v178, v100, v101
	v_add_u32_e32 v155, 0x8000, v153
	global_store_dwordx4 v155, v[178:181], s[26:27] offset:64
	s_nop 1
	v_add_u32_e32 v154, 0x48000, v153
	global_load_dwordx4 v[178:181], v154, s[26:27] offset:64
	s_waitcnt vmcnt(11)
	v_cvt_f32_f16_e32 v202, v182
	v_cvt_f32_f16_sdwa v203, v182 dst_sel:DWORD dst_unused:UNUSED_PAD src0_sel:WORD_1
	v_cvt_f32_f16_e32 v204, v183
	v_cvt_f32_f16_sdwa v205, v183 dst_sel:DWORD dst_unused:UNUSED_PAD src0_sel:WORD_1
	v_cvt_f32_f16_e32 v206, v184
	v_cvt_f32_f16_sdwa v207, v184 dst_sel:DWORD dst_unused:UNUSED_PAD src0_sel:WORD_1
	v_cvt_f32_f16_e32 v208, v185
	v_cvt_f32_f16_sdwa v209, v185 dst_sel:DWORD dst_unused:UNUSED_PAD src0_sel:WORD_1
	v_pk_fma_f32 v[94:95], v[94:95], v[130:131], v[204:205]
	v_pk_fma_f32 v[92:93], v[92:93], v[128:129], v[202:203]
	v_pk_fma_f32 v[90:91], v[90:91], v[134:135], v[208:209]
	v_pk_fma_f32 v[88:89], v[88:89], v[132:133], v[206:207]
	v_cvt_pk_f16_f32 v185, v90, v91
	v_cvt_pk_f16_f32 v184, v88, v89
	v_cvt_pk_f16_f32 v183, v94, v95
	v_cvt_pk_f16_f32 v182, v92, v93
	v_add_u32_e32 v155, 0x10000, v153
	global_store_dwordx4 v155, v[182:185], s[26:27]
	s_nop 1
	v_add_u32_e32 v154, 0x50000, v153
	global_load_dwordx4 v[182:185], v154, s[26:27]
	s_waitcnt vmcnt(12)
	v_cvt_f32_f16_e32 v202, v186
	v_cvt_f32_f16_sdwa v203, v186 dst_sel:DWORD dst_unused:UNUSED_PAD src0_sel:WORD_1
	v_cvt_f32_f16_e32 v204, v187
	v_cvt_f32_f16_sdwa v205, v187 dst_sel:DWORD dst_unused:UNUSED_PAD src0_sel:WORD_1
	v_cvt_f32_f16_e32 v206, v188
	v_cvt_f32_f16_sdwa v207, v188 dst_sel:DWORD dst_unused:UNUSED_PAD src0_sel:WORD_1
	v_cvt_f32_f16_e32 v208, v189
	v_cvt_f32_f16_sdwa v209, v189 dst_sel:DWORD dst_unused:UNUSED_PAD src0_sel:WORD_1
	v_pk_fma_f32 v[86:87], v[86:87], v[138:139], v[204:205]
	v_pk_fma_f32 v[84:85], v[84:85], v[136:137], v[202:203]
	v_pk_fma_f32 v[82:83], v[82:83], v[142:143], v[208:209]
	v_pk_fma_f32 v[80:81], v[80:81], v[140:141], v[206:207]
	v_cvt_pk_f16_f32 v189, v82, v83
	v_cvt_pk_f16_f32 v188, v80, v81
	v_cvt_pk_f16_f32 v187, v86, v87
	v_cvt_pk_f16_f32 v186, v84, v85
	v_add_u32_e32 v155, 0x10000, v153
	global_store_dwordx4 v155, v[186:189], s[26:27] offset:64
	s_nop 1
	v_add_u32_e32 v154, 0x50000, v153
	global_load_dwordx4 v[186:189], v154, s[26:27] offset:64
	s_waitcnt vmcnt(13)
;     __device__ __forceinline__ void operator()(AccRef acc, int pm, int pn, int wr, int wc, int fr, int fq) const {
;     ...
;             for (int m = 0; m < 4; ++m) { const int row = EPI_ROW(ai, m); const float* gp = gate + (size_t)(row >> 12) * 9216; const size_t ro = (size_t)row * 1024;
; #pragma unroll
;                 for (int bj = 0; bj < 2; ++bj) { const int col = pn * 256 + wc * 64 + bj * 32 + 8 * fq;
;                     const f32x4 g0 = *(const f32x4*)(gp + col), g1 = *(const f32x4*)(gp + col + 4);
;                     f32x4 x0, x1;
;                     if (mode == 0) { x0 = *(const f32x4*)(xin_f + ro + col); x1 = *(const f32x4*)(xin_f + ro + col + 4); }
;                     else { const h16x8 h = *(const h16x8*)(xh + ro + col); x0 = (f32x4){(float)h[0], (float)h[1], (float)h[2], (float)h[3]}; x1 = (f32x4){(float)h[4], (float)h[5], (float)h[6], (float)h[7]}; }
;                     const f32x4 y0 = x0 + gs * g0 * acc[ai][bj][m][0], y1 = x1 + gs * g1 * acc[ai][bj][m][1];
;                     if (mode == 2) { *(f32x4*)(xout_f + ro + col) = y0; *(f32x4*)(xout_f + ro + col + 4) = y1; }
;                     else { h16x8 h; h[0] = (_Float16)y0[0]; h[1] = (_Float16)y0[1]; h[2] = (_Float16)y0[2]; h[3] = (_Float16)y0[3]; h[4] = (_Float16)y1[0]; h[5] = (_Float16)y1[1]; h[6] = (_Float16)y1[2]; h[7] = (_Float16)y1[3];
;                         *(h16x8*)(xh + ro + col) = h; } } }
	v_cvt_f32_f16_e32 v202, v194
	v_cvt_f32_f16_sdwa v203, v194 dst_sel:DWORD dst_unused:UNUSED_PAD src0_sel:WORD_1
	v_cvt_f32_f16_e32 v204, v195
	v_cvt_f32_f16_sdwa v205, v195 dst_sel:DWORD dst_unused:UNUSED_PAD src0_sel:WORD_1
	v_cvt_f32_f16_e32 v206, v196
	v_cvt_f32_f16_sdwa v207, v196 dst_sel:DWORD dst_unused:UNUSED_PAD src0_sel:WORD_1
	v_cvt_f32_f16_e32 v208, v197
	v_cvt_f32_f16_sdwa v209, v197 dst_sel:DWORD dst_unused:UNUSED_PAD src0_sel:WORD_1
	v_pk_fma_f32 v[78:79], v[78:79], v[130:131], v[204:205]
	v_pk_fma_f32 v[76:77], v[76:77], v[128:129], v[202:203]
	v_pk_fma_f32 v[74:75], v[74:75], v[134:135], v[208:209]
	v_pk_fma_f32 v[72:73], v[72:73], v[132:133], v[206:207]
	v_cvt_pk_f16_f32 v197, v74, v75
	v_cvt_pk_f16_f32 v196, v72, v73
	v_cvt_pk_f16_f32 v195, v78, v79
	v_cvt_pk_f16_f32 v194, v76, v77
	v_add_u32_e32 v155, 0x18000, v153
	global_store_dwordx4 v155, v[194:197], s[26:27]
	s_nop 1
	v_add_u32_e32 v154, 0x58000, v153
	global_load_dwordx4 v[194:197], v154, s[26:27]
	s_waitcnt vmcnt(14)
	v_cvt_f32_f16_e32 v202, v198
	v_cvt_f32_f16_sdwa v203, v198 dst_sel:DWORD dst_unused:UNUSED_PAD src0_sel:WORD_1
	v_cvt_f32_f16_e32 v204, v199
	v_cvt_f32_f16_sdwa v205, v199 dst_sel:DWORD dst_unused:UNUSED_PAD src0_sel:WORD_1
	v_cvt_f32_f16_e32 v206, v200
	v_cvt_f32_f16_sdwa v207, v200 dst_sel:DWORD dst_unused:UNUSED_PAD src0_sel:WORD_1
	v_cvt_f32_f16_e32 v208, v201
	v_cvt_f32_f16_sdwa v209, v201 dst_sel:DWORD dst_unused:UNUSED_PAD src0_sel:WORD_1
	v_pk_fma_f32 v[70:71], v[70:71], v[138:139], v[204:205]
	v_pk_fma_f32 v[68:69], v[68:69], v[136:137], v[202:203]
	v_pk_fma_f32 v[66:67], v[66:67], v[142:143], v[208:209]
	v_pk_fma_f32 v[64:65], v[64:65], v[140:141], v[206:207]
	v_cvt_pk_f16_f32 v201, v66, v67
	v_cvt_pk_f16_f32 v200, v64, v65
	v_cvt_pk_f16_f32 v199, v70, v71
	v_cvt_pk_f16_f32 v198, v68, v69
	v_add_u32_e32 v155, 0x18000, v153
	global_store_dwordx4 v155, v[198:201], s[26:27] offset:64
	s_nop 1
	v_add_u32_e32 v154, 0x58000, v153
	global_load_dwordx4 v[198:201], v154, s[26:27] offset:64
	s_waitcnt vmcnt(14)
	v_cvt_f32_f16_e32 v202, v166
	v_cvt_f32_f16_sdwa v203, v166 dst_sel:DWORD dst_unused:UNUSED_PAD src0_sel:WORD_1
	v_cvt_f32_f16_e32 v204, v167
	v_cvt_f32_f16_sdwa v205, v167 dst_sel:DWORD dst_unused:UNUSED_PAD src0_sel:WORD_1
	v_cvt_f32_f16_e32 v206, v168
	v_cvt_f32_f16_sdwa v207, v168 dst_sel:DWORD dst_unused:UNUSED_PAD src0_sel:WORD_1
	v_cvt_f32_f16_e32 v208, v169
	v_cvt_f32_f16_sdwa v209, v169 dst_sel:DWORD dst_unused:UNUSED_PAD src0_sel:WORD_1
	v_pk_fma_f32 v[62:63], v[62:63], v[130:131], v[204:205]
	v_pk_fma_f32 v[60:61], v[60:61], v[128:129], v[202:203]
	v_pk_fma_f32 v[58:59], v[58:59], v[134:135], v[208:209]
	v_pk_fma_f32 v[56:57], v[56:57], v[132:133], v[206:207]
	v_cvt_pk_f16_f32 v169, v58, v59
	v_cvt_pk_f16_f32 v168, v56, v57
	v_cvt_pk_f16_f32 v167, v62, v63
	v_cvt_pk_f16_f32 v166, v60, v61
	v_add_u32_e32 v155, 0x40000, v153
	global_store_dwordx4 v155, v[166:169], s[26:27]
	s_waitcnt vmcnt(13)
	v_cvt_f32_f16_e32 v202, v170
	v_cvt_f32_f16_sdwa v203, v170 dst_sel:DWORD dst_unused:UNUSED_PAD src0_sel:WORD_1
	v_cvt_f32_f16_e32 v204, v171
	v_cvt_f32_f16_sdwa v205, v171 dst_sel:DWORD dst_unused:UNUSED_PAD src0_sel:WORD_1
	v_cvt_f32_f16_e32 v206, v172
	v_cvt_f32_f16_sdwa v207, v172 dst_sel:DWORD dst_unused:UNUSED_PAD src0_sel:WORD_1
	v_cvt_f32_f16_e32 v208, v173
	v_cvt_f32_f16_sdwa v209, v173 dst_sel:DWORD dst_unused:UNUSED_PAD src0_sel:WORD_1
	v_pk_fma_f32 v[54:55], v[54:55], v[138:139], v[204:205]
	v_pk_fma_f32 v[52:53], v[52:53], v[136:137], v[202:203]
	v_pk_fma_f32 v[50:51], v[50:51], v[142:143], v[208:209]
	v_pk_fma_f32 v[48:49], v[48:49], v[140:141], v[206:207]
	v_cvt_pk_f16_f32 v173, v50, v51
	v_cvt_pk_f16_f32 v172, v48, v49
	v_cvt_pk_f16_f32 v171, v54, v55
	v_cvt_pk_f16_f32 v170, v52, v53
	v_add_u32_e32 v155, 0x40000, v153
	global_store_dwordx4 v155, v[170:173], s[26:27] offset:64
	s_waitcnt vmcnt(12)
	v_cvt_f32_f16_e32 v202, v174
	v_cvt_f32_f16_sdwa v203, v174 dst_sel:DWORD dst_unused:UNUSED_PAD src0_sel:WORD_1
	v_cvt_f32_f16_e32 v204, v175
	v_cvt_f32_f16_sdwa v205, v175 dst_sel:DWORD dst_unused:UNUSED_PAD src0_sel:WORD_1
	v_cvt_f32_f16_e32 v206, v176
	v_cvt_f32_f16_sdwa v207, v176 dst_sel:DWORD dst_unused:UNUSED_PAD src0_sel:WORD_1
	v_cvt_f32_f16_e32 v208, v177
	v_cvt_f32_f16_sdwa v209, v177 dst_sel:DWORD dst_unused:UNUSED_PAD src0_sel:WORD_1
	v_pk_fma_f32 v[46:47], v[46:47], v[130:131], v[204:205]
	v_pk_fma_f32 v[44:45], v[44:45], v[128:129], v[202:203]
	v_pk_fma_f32 v[42:43], v[42:43], v[134:135], v[208:209]
	v_pk_fma_f32 v[40:41], v[40:41], v[132:133], v[206:207]
	v_cvt_pk_f16_f32 v177, v42, v43
	v_cvt_pk_f16_f32 v176, v40, v41
	v_cvt_pk_f16_f32 v175, v46, v47
	v_cvt_pk_f16_f32 v174, v44, v45
	v_add_u32_e32 v155, 0x48000, v153
	global_store_dwordx4 v155, v[174:177], s[26:27]
	s_waitcnt vmcnt(11)
;     __device__ __forceinline__ void operator()(AccRef acc, int pm, int pn, int wr, int wc, int fr, int fq) const {
;     ...
;             for (int m = 0; m < 4; ++m) { const int row = EPI_ROW(ai, m); const float* gp = gate + (size_t)(row >> 12) * 9216; const size_t ro = (size_t)row * 1024;
; #pragma unroll
;                 for (int bj = 0; bj < 2; ++bj) { const int col = pn * 256 + wc * 64 + bj * 32 + 8 * fq;
;                     const f32x4 g0 = *(const f32x4*)(gp + col), g1 = *(const f32x4*)(gp + col + 4);
;                     f32x4 x0, x1;
;                     if (mode == 0) { x0 = *(const f32x4*)(xin_f + ro + col); x1 = *(const f32x4*)(xin_f + ro + col + 4); }
;                     else { const h16x8 h = *(const h16x8*)(xh + ro + col); x0 = (f32x4){(float)h[0], (float)h[1], (float)h[2], (float)h[3]}; x1 = (f32x4){(float)h[4], (float)h[5], (float)h[6], (float)h[7]}; }
;                     const f32x4 y0 = x0 + gs * g0 * acc[ai][bj][m][0], y1 = x1 + gs * g1 * acc[ai][bj][m][1];
;                     if (mode == 2) { *(f32x4*)(xout_f + ro + col) = y0; *(f32x4*)(xout_f + ro + col + 4) = y1; }
;                     else { h16x8 h; h[0] = (_Float16)y0[0]; h[1] = (_Float16)y0[1]; h[2] = (_Float16)y0[2]; h[3] = (_Float16)y0[3]; h[4] = (_Float16)y1[0]; h[5] = (_Float16)y1[1]; h[6] = (_Float16)y1[2]; h[7] = (_Float16)y1[3];
;                         *(h16x8*)(xh + ro + col) = h; } } }
	v_cvt_f32_f16_e32 v202, v178
	v_cvt_f32_f16_sdwa v203, v178 dst_sel:DWORD dst_unused:UNUSED_PAD src0_sel:WORD_1
	v_cvt_f32_f16_e32 v204, v179
	v_cvt_f32_f16_sdwa v205, v179 dst_sel:DWORD dst_unused:UNUSED_PAD src0_sel:WORD_1
	v_cvt_f32_f16_e32 v206, v180
	v_cvt_f32_f16_sdwa v207, v180 dst_sel:DWORD dst_unused:UNUSED_PAD src0_sel:WORD_1
	v_cvt_f32_f16_e32 v208, v181
	v_cvt_f32_f16_sdwa v209, v181 dst_sel:DWORD dst_unused:UNUSED_PAD src0_sel:WORD_1
	v_pk_fma_f32 v[38:39], v[38:39], v[138:139], v[204:205]
	v_pk_fma_f32 v[36:37], v[36:37], v[136:137], v[202:203]
	v_pk_fma_f32 v[34:35], v[34:35], v[142:143], v[208:209]
	v_pk_fma_f32 v[32:33], v[32:33], v[140:141], v[206:207]
	v_cvt_pk_f16_f32 v181, v34, v35
	v_cvt_pk_f16_f32 v180, v32, v33
	v_cvt_pk_f16_f32 v179, v38, v39
	v_cvt_pk_f16_f32 v178, v36, v37
	v_add_u32_e32 v155, 0x48000, v153
	global_store_dwordx4 v155, v[178:181], s[26:27] offset:64
	s_waitcnt vmcnt(10)
	v_cvt_f32_f16_e32 v202, v182
	v_cvt_f32_f16_sdwa v203, v182 dst_sel:DWORD dst_unused:UNUSED_PAD src0_sel:WORD_1
	v_cvt_f32_f16_e32 v204, v183
	v_cvt_f32_f16_sdwa v205, v183 dst_sel:DWORD dst_unused:UNUSED_PAD src0_sel:WORD_1
	v_cvt_f32_f16_e32 v206, v184
	v_cvt_f32_f16_sdwa v207, v184 dst_sel:DWORD dst_unused:UNUSED_PAD src0_sel:WORD_1
	v_cvt_f32_f16_e32 v208, v185
	v_cvt_f32_f16_sdwa v209, v185 dst_sel:DWORD dst_unused:UNUSED_PAD src0_sel:WORD_1
	v_pk_fma_f32 v[30:31], v[30:31], v[130:131], v[204:205]
	v_pk_fma_f32 v[28:29], v[28:29], v[128:129], v[202:203]
	v_pk_fma_f32 v[26:27], v[26:27], v[134:135], v[208:209]
	v_pk_fma_f32 v[24:25], v[24:25], v[132:133], v[206:207]
	v_cvt_pk_f16_f32 v185, v26, v27
	v_cvt_pk_f16_f32 v184, v24, v25
	v_cvt_pk_f16_f32 v183, v30, v31
	v_cvt_pk_f16_f32 v182, v28, v29
	v_add_u32_e32 v155, 0x50000, v153
	global_store_dwordx4 v155, v[182:185], s[26:27]
	s_waitcnt vmcnt(9)
	v_cvt_f32_f16_e32 v202, v186
	v_cvt_f32_f16_sdwa v203, v186 dst_sel:DWORD dst_unused:UNUSED_PAD src0_sel:WORD_1
	v_cvt_f32_f16_e32 v204, v187
	v_cvt_f32_f16_sdwa v205, v187 dst_sel:DWORD dst_unused:UNUSED_PAD src0_sel:WORD_1
	v_cvt_f32_f16_e32 v206, v188
	v_cvt_f32_f16_sdwa v207, v188 dst_sel:DWORD dst_unused:UNUSED_PAD src0_sel:WORD_1
	v_cvt_f32_f16_e32 v208, v189
	v_cvt_f32_f16_sdwa v209, v189 dst_sel:DWORD dst_unused:UNUSED_PAD src0_sel:WORD_1
	v_pk_fma_f32 v[22:23], v[22:23], v[138:139], v[204:205]
	v_pk_fma_f32 v[20:21], v[20:21], v[136:137], v[202:203]
	v_pk_fma_f32 v[18:19], v[18:19], v[142:143], v[208:209]
	v_pk_fma_f32 v[16:17], v[16:17], v[140:141], v[206:207]
	v_cvt_pk_f16_f32 v189, v18, v19
	v_cvt_pk_f16_f32 v188, v16, v17
	v_cvt_pk_f16_f32 v187, v22, v23
	v_cvt_pk_f16_f32 v186, v20, v21
	v_add_u32_e32 v155, 0x50000, v153
	global_store_dwordx4 v155, v[186:189], s[26:27] offset:64
	s_waitcnt vmcnt(8)
	v_cvt_f32_f16_e32 v202, v194
	v_cvt_f32_f16_sdwa v203, v194 dst_sel:DWORD dst_unused:UNUSED_PAD src0_sel:WORD_1
	v_cvt_f32_f16_e32 v204, v195
	v_cvt_f32_f16_sdwa v205, v195 dst_sel:DWORD dst_unused:UNUSED_PAD src0_sel:WORD_1
	v_cvt_f32_f16_e32 v206, v196
	v_cvt_f32_f16_sdwa v207, v196 dst_sel:DWORD dst_unused:UNUSED_PAD src0_sel:WORD_1
	v_cvt_f32_f16_e32 v208, v197
	v_cvt_f32_f16_sdwa v209, v197 dst_sel:DWORD dst_unused:UNUSED_PAD src0_sel:WORD_1
	v_pk_fma_f32 v[14:15], v[14:15], v[130:131], v[204:205]
	v_pk_fma_f32 v[12:13], v[12:13], v[128:129], v[202:203]
	v_pk_fma_f32 v[10:11], v[10:11], v[134:135], v[208:209]
	v_pk_fma_f32 v[8:9], v[8:9], v[132:133], v[206:207]
	v_cvt_pk_f16_f32 v197, v10, v11
	v_cvt_pk_f16_f32 v196, v8, v9
	v_cvt_pk_f16_f32 v195, v14, v15
	v_cvt_pk_f16_f32 v194, v12, v13
	v_add_u32_e32 v155, 0x58000, v153
	global_store_dwordx4 v155, v[194:197], s[26:27]
	s_waitcnt vmcnt(7)
	v_cvt_f32_f16_e32 v202, v198
	v_cvt_f32_f16_sdwa v203, v198 dst_sel:DWORD dst_unused:UNUSED_PAD src0_sel:WORD_1
	v_cvt_f32_f16_e32 v204, v199
	v_cvt_f32_f16_sdwa v205, v199 dst_sel:DWORD dst_unused:UNUSED_PAD src0_sel:WORD_1
	v_cvt_f32_f16_e32 v206, v200
	v_cvt_f32_f16_sdwa v207, v200 dst_sel:DWORD dst_unused:UNUSED_PAD src0_sel:WORD_1
	v_cvt_f32_f16_e32 v208, v201
	v_cvt_f32_f16_sdwa v209, v201 dst_sel:DWORD dst_unused:UNUSED_PAD src0_sel:WORD_1
	v_pk_fma_f32 v[6:7], v[6:7], v[138:139], v[204:205]
	v_pk_fma_f32 v[4:5], v[4:5], v[136:137], v[202:203]
	v_pk_fma_f32 v[2:3], v[2:3], v[142:143], v[208:209]
	v_pk_fma_f32 v[0:1], v[0:1], v[140:141], v[206:207]
	v_cvt_pk_f16_f32 v201, v2, v3
	v_cvt_pk_f16_f32 v200, v0, v1
	v_cvt_pk_f16_f32 v199, v6, v7
	v_cvt_pk_f16_f32 v198, v4, v5
	v_add_u32_e32 v155, 0x58000, v153
	global_store_dwordx4 v155, v[198:201], s[26:27] offset:64
	s_branch .LBB0_46
.Lepi_ffo_slow:
	v_ashrrev_i32_e32 v128, 12, v152
	v_mul_hi_i32_i24_e32 v129, 0x9000, v128
	v_mul_i32_i24_e32 v128, 0x9000, v128
	v_lshl_add_u64 v[128:129], s[50:51], 0, v[128:129]
	v_ashrrev_i32_e32 v151, 31, v150
	v_lshl_add_u64 v[158:159], v[150:151], 2, v[128:129]
	flat_load_dwordx4 v[136:139], v[158:159]
	flat_load_dwordx4 v[128:131], v[158:159] offset:16
	v_ashrrev_i32_e32 v153, 31, v152
	v_lshlrev_b64 v[160:161], 10, v[152:153]
	s_mov_b64 s[40:41], -1
	s_andn2_b64 vcc, exec, s[36:37]
	v_lshl_add_u64 v[156:157], v[160:161], 2, s[42:43]
	s_cbranch_vccnz .LBB0_57
	v_lshl_add_u64 v[140:141], v[150:151], 2, v[156:157]
	global_load_dwordx4 v[132:135], v[140:141], off offset:16
	s_nop 0
	global_load_dwordx4 v[140:143], v[140:141], off
	s_mov_b64 s[40:41], 0

; __device__ __forceinline__ unsigned cvt_pk_bf16(float lo, float hi) { unsigned r; asm volatile("v_cvt_pk_bf16_f32 %0, %1, %2" : "=v"(r) : "v"(lo), "v"(hi)); return r; }
; __device__ __forceinline__ float fq_sum(float x) { float a = x, b = x; pl16(a, b); float y = a + b, c = y; pl32(y, c); return y + c; }
; __device__ __forceinline__ void phase_attn_a(const bf16_t* Qb, const bf16_t* Kb, const bf16_t* Vt, bf16_t* O, const float* lam, const float* subg, const float* qg, const float* kg, float lam_init, LAS unsigned char* lds, int wv) {
;     ...
;         if (cm == 0) {
; #pragma unroll
;             for (int qb = 0; qb < 2; ++qb) { float ss = 0.f;
; #pragma unroll
;                 for (int db = 0; db < 8; ++db) { const f32x4 o1 = xb[(g * 16 + db * 2 + qb) * 64 + lane]; const f32x4 v = oacc[db][qb] - lam_full * o1; oacc[db][qb] = v;
;                     ss += (v[0] * v[0] + v[1] * v[1]) + (v[2] * v[2] + v[3] * v[3]); }
;                 ss = fq_sum(ss);
;                 const float rinv = rsqrtf(ss * (1.0f / 128.0f) + 1e-5f) * (1.0f - lam_init);
;                 bf16_t* rp = O + (size_t)(b * T + q0 + qb * 16 + cfr) * 1024 + hh * 128 + 8 * cfq;
; #pragma unroll
;                 for (int e = 0; e < 4; ++e) {
;                     const f32x4 g0 = *(const f32x4*)(subg + e * 32 + 8 * cfq), g1 = *(const f32x4*)(subg + e * 32 + 8 * cfq + 4);
;                     const f32x4 v0 = oacc[2 * e][qb] * rinv * g0, v1 = oacc[2 * e + 1][qb] * rinv * g1;
;                     u32x4 w; w.x = cvt_pk_bf16(v0[0], v0[1]); w.y = cvt_pk_bf16(v0[2], v0[3]); w.z = cvt_pk_bf16(v1[0], v1[1]); w.w = cvt_pk_bf16(v1[2], v1[3]); *(u32x4*)(rp + e * 32) = w; } }
.LBB0_1966:
	s_andn2_b64 vcc, exec, s[76:77]
	s_waitcnt lgkmcnt(0)
	s_barrier
	s_cbranch_vccnz .LBB0_1951
	ds_read_b128 v[70:73], v236
	s_xor_b32 s39, s59, 0x80000000
	s_xor_b32 s38, s58, 0x80000000
	v_add_u32_e32 v66, s71, v129
	v_lshlrev_b32_e32 v64, 3, v128
	s_waitcnt lgkmcnt(0)
	v_pk_fma_f32 v[62:63], s[38:39], v[72:73], v[62:63]
	v_pk_fma_f32 v[60:61], s[20:21], v[70:71], v[60:61] neg_lo:[1,0,0] neg_hi:[1,0,0]
	ds_read_b128 v[70:73], v236 offset:2048
	v_mov_b32_e32 v74, v63
	v_ashrrev_i32_e32 v65, 31, v64
	v_ashrrev_i32_e32 v67, 31, v66
	v_lshl_add_u64 v[68:69], v[64:65], 1, s[52:53]
	s_waitcnt lgkmcnt(0)
	v_pk_fma_f32 v[70:71], s[20:21], v[70:71], v[56:57] neg_lo:[1,0,0] neg_hi:[1,0,0]
	v_pk_fma_f32 v[58:59], s[38:39], v[72:73], v[58:59]
	v_mov_b32_e32 v72, v61
	v_mov_b32_e32 v73, v71
	v_mov_b32_e32 v56, v60
	v_mov_b32_e32 v57, v70
	v_pk_mul_f32 v[72:73], v[72:73], v[72:73]
	v_mov_b32_e32 v75, v59
	v_pk_fma_f32 v[56:57], v[56:57], v[56:57], v[72:73]
	v_mov_b32_e32 v72, v62
	v_mov_b32_e32 v73, v58
	v_pk_mul_f32 v[74:75], v[74:75], v[74:75]
	v_lshl_add_u64 v[64:65], v[64:65], 2, s[36:37]
	v_pk_fma_f32 v[72:73], v[72:73], v[72:73], v[74:75]
	s_nop 0
	v_pk_add_f32 v[76:77], v[56:57], v[72:73]
	ds_read_b128 v[72:75], v236 offset:4096
	s_waitcnt lgkmcnt(0)
	v_pk_fma_f32 v[56:57], s[38:39], v[74:75], v[54:55]
	v_pk_fma_f32 v[72:73], s[20:21], v[72:73], v[52:53] neg_lo:[1,0,0] neg_hi:[1,0,0]
	v_pk_mul_f32 v[54:55], v[56:57], v[56:57]
	v_pk_mul_f32 v[52:53], v[72:73], v[72:73]
	s_nop 0
	v_pk_mov_b32 v[74:75], v[52:53], v[54:55] op_sel:[1,0]
	v_mov_b32_e32 v53, v55
	v_pk_add_f32 v[74:75], v[74:75], v[52:53]
	ds_read_b128 v[52:55], v236 offset:6144
	s_waitcnt lgkmcnt(0)
	v_pk_fma_f32 v[78:79], s[38:39], v[54:55], v[42:43]
	v_pk_fma_f32 v[80:81], s[20:21], v[52:53], v[40:41] neg_lo:[1,0,0] neg_hi:[1,0,0]
	ds_read_b128 v[40:43], v236 offset:8192
	s_waitcnt lgkmcnt(0)
	v_pk_fma_f32 v[54:55], s[20:21], v[40:41], v[44:45] neg_lo:[1,0,0] neg_hi:[1,0,0]
	v_pk_fma_f32 v[52:53], s[38:39], v[42:43], v[46:47]
	v_mul_f32_e32 v42, v54, v54
	v_pk_add_f32 v[40:41], v[76:77], v[76:77] op_sel:[0,1] op_sel_hi:[1,0]
	v_mul_f32_e32 v44, v55, v55
	v_mov_b32_e32 v41, v42
	v_pk_add_f32 v[42:43], v[74:75], v[74:75] op_sel:[0,1] op_sel_hi:[1,0]
	v_mul_f32_e32 v45, v52, v52
	v_mov_b32_e32 v43, v44
	v_pk_add_f32 v[40:41], v[40:41], v[42:43]
	v_mul_f32_e32 v42, v81, v81
	v_pk_fma_f32 v[42:43], v[80:81], v[80:81], v[42:43] op_sel_hi:[1,1,0]
	v_mul_f32_e32 v44, v79, v79
	v_mul_f32_e32 v46, v53, v53
	v_mov_b32_e32 v43, v45
	v_pk_fma_f32 v[44:45], v[78:79], v[78:79], v[44:45] op_sel_hi:[1,1,0]
	s_nop 0
	v_mov_b32_e32 v45, v46
	v_pk_add_f32 v[42:43], v[42:43], v[44:45]
	s_nop 0
	v_pk_add_f32 v[82:83], v[40:41], v[42:43]
	ds_read_b128 v[40:43], v236 offset:10240
	s_waitcnt lgkmcnt(0)
	v_pk_fma_f32 v[74:75], s[38:39], v[42:43], v[38:39]
	v_pk_fma_f32 v[76:77], s[20:21], v[40:41], v[36:37] neg_lo:[1,0,0] neg_hi:[1,0,0]
	v_pk_mul_f32 v[38:39], v[74:75], v[74:75]
	v_pk_mul_f32 v[36:37], v[76:77], v[76:77]
	s_nop 0
	v_pk_mov_b32 v[40:41], v[36:37], v[38:39] op_sel:[1,0]
	v_mov_b32_e32 v37, v39
	v_pk_add_f32 v[84:85], v[40:41], v[36:37]
	ds_read_b128 v[36:39], v236 offset:12288
	s_waitcnt lgkmcnt(0)
	v_pk_fma_f32 v[42:43], s[38:39], v[38:39], v[34:35]
	v_pk_fma_f32 v[46:47], s[20:21], v[36:37], v[32:33] neg_lo:[1,0,0] neg_hi:[1,0,0]
	ds_read_b128 v[32:35], v236 offset:14336
	s_waitcnt lgkmcnt(0)
	v_pk_fma_f32 v[44:45], s[20:21], v[32:33], v[48:49] neg_lo:[1,0,0] neg_hi:[1,0,0]
	v_pk_fma_f32 v[40:41], s[38:39], v[34:35], v[50:51]
	v_mul_f32_e32 v34, v44, v44
	v_pk_add_f32 v[32:33], v[82:83], v[82:83] op_sel:[0,1] op_sel_hi:[1,0]
	v_mul_f32_e32 v36, v45, v45
	v_mov_b32_e32 v33, v34
	v_pk_add_f32 v[34:35], v[84:85], v[84:85] op_sel:[0,1] op_sel_hi:[1,0]
	v_mul_f32_e32 v37, v40, v40
	v_mov_b32_e32 v35, v36
	v_pk_add_f32 v[32:33], v[32:33], v[34:35]
	v_mul_f32_e32 v34, v47, v47
	v_pk_fma_f32 v[34:35], v[46:47], v[46:47], v[34:35] op_sel_hi:[1,1,0]
	v_mul_f32_e32 v36, v43, v43
	v_mul_f32_e32 v38, v41, v41
	v_mov_b32_e32 v35, v37
	v_pk_fma_f32 v[36:37], v[42:43], v[42:43], v[36:37] op_sel_hi:[1,1,0]
	v_mov_b32_e32 v51, 0x3727c5ac
	v_mov_b32_e32 v37, v38
	v_pk_add_f32 v[34:35], v[34:35], v[36:37]
	s_nop 0
	v_pk_add_f32 v[32:33], v[32:33], v[34:35]
	s_nop 0
	v_add_f32_e32 v32, v32, v33
	v_mov_b32_e32 v33, v32
	s_nop 1
	v_permlane16_swap_b32 v33, v32
	s_nop 0
	v_add_f32_e32 v32, v33, v32
	v_mov_b32_e32 v33, v32
	s_nop 1
	v_permlane32_swap_b32 v33, v32
	s_nop 0
	v_add_f32_e32 v32, v33, v32
	v_fmamk_f32 v32, v32, 0x3c000000, v51
	v_cmp_gt_f32_e32 vcc, s2, v32
	v_mul_f32_e32 v33, 0x4b800000, v32
	s_nop 0
	v_cndmask_b32_e32 v32, v32, v33, vcc
	v_rsq_f32_e32 v32, v32
	s_nop 0
	v_mul_f32_e32 v33, 0x45800000, v32
	v_cndmask_b32_e32 v32, v32, v33, vcc
	v_mul_f32_e32 v50, v234, v32
	v_lshlrev_b64 v[32:33], 11, v[66:67]
	v_lshl_add_u64 v[48:49], v[68:69], 0, v[32:33]
	global_load_dwordx4 v[32:35], v[64:65], off offset:16
	global_load_dwordx4 v[36:39], v[64:65], off
	v_pk_mul_f32 v[60:61], v[60:61], v[50:51] op_sel_hi:[1,0]
	v_pk_mul_f32 v[58:59], v[58:59], v[50:51] op_sel_hi:[1,0]
	v_pk_mul_f32 v[62:63], v[62:63], v[50:51] op_sel_hi:[1,0]
	v_pk_mul_f32 v[56:57], v[56:57], v[50:51] op_sel_hi:[1,0]
	v_pk_mul_f32 v[54:55], v[54:55], v[50:51] op_sel_hi:[1,0]
	v_pk_mul_f32 v[52:53], v[52:53], v[50:51] op_sel_hi:[1,0]
	v_pk_mul_f32 v[42:43], v[42:43], v[50:51] op_sel_hi:[1,0]
	v_pk_mul_f32 v[40:41], v[40:41], v[50:51] op_sel_hi:[1,0]
	v_pk_mul_f32 v[46:47], v[46:47], v[50:51] op_sel_hi:[1,0]
	s_waitcnt vmcnt(1)
	v_pk_mul_f32 v[58:59], v[34:35], v[58:59]
	s_waitcnt vmcnt(0)
; __device__ __forceinline__ unsigned cvt_pk_bf16(float lo, float hi) { unsigned r; asm volatile("v_cvt_pk_bf16_f32 %0, %1, %2" : "=v"(r) : "v"(lo), "v"(hi)); return r; }
; __device__ __forceinline__ float fq_sum(float x) { float a = x, b = x; pl16(a, b); float y = a + b, c = y; pl32(y, c); return y + c; }
; __device__ __forceinline__ void phase_attn_a(const bf16_t* Qb, const bf16_t* Kb, const bf16_t* Vt, bf16_t* O, const float* lam, const float* subg, const float* qg, const float* kg, float lam_init, LAS unsigned char* lds, int wv) {
;     ...
;                 for (int db = 0; db < 8; ++db) { const f32x4 o1 = xb[(g * 16 + db * 2 + qb) * 64 + lane]; const f32x4 v = oacc[db][qb] - lam_full * o1; oacc[db][qb] = v;
;                     ss += (v[0] * v[0] + v[1] * v[1]) + (v[2] * v[2] + v[3] * v[3]); }
;                 ss = fq_sum(ss);
;                 const float rinv = rsqrtf(ss * (1.0f / 128.0f) + 1e-5f) * (1.0f - lam_init);
;                 bf16_t* rp = O + (size_t)(b * T + q0 + qb * 16 + cfr) * 1024 + hh * 128 + 8 * cfq;
; #pragma unroll
;                 for (int e = 0; e < 4; ++e) {
;                     const f32x4 g0 = *(const f32x4*)(subg + e * 32 + 8 * cfq), g1 = *(const f32x4*)(subg + e * 32 + 8 * cfq + 4);
;                     const f32x4 v0 = oacc[2 * e][qb] * rinv * g0, v1 = oacc[2 * e + 1][qb] * rinv * g1;
;                     u32x4 w; w.x = cvt_pk_bf16(v0[0], v0[1]); w.y = cvt_pk_bf16(v0[2], v0[3]); w.z = cvt_pk_bf16(v1[0], v1[1]); w.w = cvt_pk_bf16(v1[2], v1[3]); *(u32x4*)(rp + e * 32) = w; } }
	v_pk_mul_f32 v[36:37], v[36:37], v[60:61]
	v_pk_mul_f32 v[60:61], v[70:71], v[50:51] op_sel_hi:[1,0]
	v_pk_mul_f32 v[38:39], v[38:39], v[62:63]
	v_pk_mul_f32 v[34:35], v[32:33], v[60:61]
	v_cvt_pk_bf16_f32 v32, v36, v37
	v_cvt_pk_bf16_f32 v33, v38, v39
	s_nop 0
	v_cvt_pk_bf16_f32 v34, v34, v35
	v_cvt_pk_bf16_f32 v35, v58, v59
	global_store_dwordx4 v[48:49], v[32:35], off
	global_load_dwordx4 v[32:35], v[64:65], off offset:144
	s_nop 0
	global_load_dwordx4 v[36:39], v[64:65], off offset:128
	v_pk_mul_f32 v[58:59], v[72:73], v[50:51] op_sel_hi:[1,0]
	s_waitcnt vmcnt(0)
	v_pk_mul_f32 v[38:39], v[38:39], v[56:57]
	v_pk_mul_f32 v[36:37], v[36:37], v[58:59]
	v_pk_mul_f32 v[56:57], v[80:81], v[50:51] op_sel_hi:[1,0]
	v_pk_mul_f32 v[58:59], v[78:79], v[50:51] op_sel_hi:[1,0]
	s_nop 0
	v_pk_mul_f32 v[58:59], v[34:35], v[58:59]
	v_pk_mul_f32 v[34:35], v[32:33], v[56:57]
	v_cvt_pk_bf16_f32 v32, v36, v37
	v_cvt_pk_bf16_f32 v33, v38, v39
	s_nop 0
	v_cvt_pk_bf16_f32 v34, v34, v35
	v_cvt_pk_bf16_f32 v35, v58, v59
	global_store_dwordx4 v[48:49], v[32:35], off offset:64
	global_load_dwordx4 v[32:35], v[64:65], off offset:272
	s_nop 0
	global_load_dwordx4 v[36:39], v[64:65], off offset:256
	s_waitcnt vmcnt(0)
	v_pk_mul_f32 v[38:39], v[52:53], v[38:39]
	v_pk_mul_f32 v[36:37], v[54:55], v[36:37]
	v_pk_mul_f32 v[52:53], v[76:77], v[50:51] op_sel_hi:[1,0]
	v_pk_mul_f32 v[54:55], v[74:75], v[50:51] op_sel_hi:[1,0]
	s_nop 0
	v_pk_mul_f32 v[54:55], v[54:55], v[34:35]
	v_pk_mul_f32 v[34:35], v[52:53], v[32:33]
	v_cvt_pk_bf16_f32 v32, v36, v37
	v_cvt_pk_bf16_f32 v33, v38, v39
	s_nop 0
	v_cvt_pk_bf16_f32 v34, v34, v35
	v_cvt_pk_bf16_f32 v35, v54, v55
	global_store_dwordx4 v[48:49], v[32:35], off offset:128
	global_load_dwordx4 v[32:35], v[64:65], off offset:400
	s_nop 0
	global_load_dwordx4 v[36:39], v[64:65], off offset:384
	s_waitcnt vmcnt(0)
	v_pk_mul_f32 v[40:41], v[40:41], v[34:35]
	v_pk_mul_f32 v[38:39], v[42:43], v[38:39]
	v_pk_mul_f32 v[42:43], v[44:45], v[50:51] op_sel_hi:[1,0]
	v_pk_mul_f32 v[36:37], v[46:47], v[36:37]
	v_pk_mul_f32 v[34:35], v[42:43], v[32:33]
	v_cvt_pk_bf16_f32 v32, v36, v37
	v_cvt_pk_bf16_f32 v33, v38, v39
	s_nop 0
	v_cvt_pk_bf16_f32 v34, v34, v35
	v_cvt_pk_bf16_f32 v35, v40, v41
	global_store_dwordx4 v[48:49], v[32:35], off offset:192
	ds_read_b128 v[32:35], v236 offset:1024
	s_waitcnt lgkmcnt(0)
	v_pk_fma_f32 v[40:41], s[38:39], v[34:35], v[22:23]
	v_pk_fma_f32 v[42:43], s[20:21], v[32:33], v[20:21] neg_lo:[1,0,0] neg_hi:[1,0,0]
	ds_read_b128 v[20:23], v236 offset:3072
	s_waitcnt lgkmcnt(0)
	v_pk_fma_f32 v[38:39], s[20:21], v[20:21], v[28:29] neg_lo:[1,0,0] neg_hi:[1,0,0]
	v_pk_fma_f32 v[36:37], s[38:39], v[22:23], v[30:31]
	v_mov_b32_e32 v22, v43
	v_mov_b32_e32 v23, v39
	v_mov_b32_e32 v20, v42
	v_mov_b32_e32 v21, v38
	v_pk_mul_f32 v[22:23], v[22:23], v[22:23]
	v_mov_b32_e32 v28, v41
	v_mov_b32_e32 v29, v37
	v_pk_fma_f32 v[20:21], v[20:21], v[20:21], v[22:23]
	v_mov_b32_e32 v22, v40
	v_mov_b32_e32 v23, v36
	v_pk_mul_f32 v[28:29], v[28:29], v[28:29]
	s_nop 0
	v_pk_fma_f32 v[22:23], v[22:23], v[22:23], v[28:29]
	s_nop 0
	v_pk_add_f32 v[44:45], v[20:21], v[22:23]
	ds_read_b128 v[20:23], v236 offset:5120
	s_waitcnt lgkmcnt(0)
	v_pk_fma_f32 v[32:33], s[38:39], v[22:23], v[18:19]
	v_pk_fma_f32 v[34:35], s[20:21], v[20:21], v[16:17] neg_lo:[1,0,0] neg_hi:[1,0,0]
	v_pk_mul_f32 v[18:19], v[32:33], v[32:33]
	v_pk_mul_f32 v[16:17], v[34:35], v[34:35]
	s_nop 0
	v_pk_mov_b32 v[20:21], v[16:17], v[18:19] op_sel:[1,0]
	v_mov_b32_e32 v17, v19
	v_pk_add_f32 v[22:23], v[20:21], v[16:17]
	ds_read_b128 v[16:19], v236 offset:7168
	s_waitcnt lgkmcnt(0)
	v_pk_fma_f32 v[28:29], s[38:39], v[18:19], v[14:15]
	v_pk_fma_f32 v[30:31], s[20:21], v[16:17], v[12:13] neg_lo:[1,0,0] neg_hi:[1,0,0]
	ds_read_b128 v[12:15], v236 offset:9216
	s_waitcnt lgkmcnt(0)
	v_pk_fma_f32 v[20:21], s[20:21], v[12:13], v[24:25] neg_lo:[1,0,0] neg_hi:[1,0,0]
	v_pk_fma_f32 v[18:19], s[38:39], v[14:15], v[26:27]
	v_mul_f32_e32 v14, v20, v20
	v_pk_add_f32 v[12:13], v[44:45], v[44:45] op_sel:[0,1] op_sel_hi:[1,0]
	v_mul_f32_e32 v16, v21, v21
	v_mov_b32_e32 v13, v14
	v_pk_add_f32 v[14:15], v[22:23], v[22:23] op_sel:[0,1] op_sel_hi:[1,0]
	v_mul_f32_e32 v17, v18, v18
	v_mov_b32_e32 v15, v16
	v_pk_add_f32 v[12:13], v[12:13], v[14:15]
	v_mul_f32_e32 v14, v31, v31
	v_pk_fma_f32 v[14:15], v[30:31], v[30:31], v[14:15] op_sel_hi:[1,1,0]
	v_mul_f32_e32 v16, v29, v29
	v_mul_f32_e32 v24, v19, v19
	v_mov_b32_e32 v15, v17
	v_pk_fma_f32 v[16:17], v[28:29], v[28:29], v[16:17] op_sel_hi:[1,1,0]
	s_nop 0
	v_mov_b32_e32 v17, v24
	v_pk_add_f32 v[14:15], v[14:15], v[16:17]
	s_nop 0
	v_pk_add_f32 v[16:17], v[12:13], v[14:15]
	ds_read_b128 v[12:15], v236 offset:11264
	s_waitcnt lgkmcnt(0)
; __device__ __forceinline__ unsigned cvt_pk_bf16(float lo, float hi) { unsigned r; asm volatile("v_cvt_pk_bf16_f32 %0, %1, %2" : "=v"(r) : "v"(lo), "v"(hi)); return r; }
; __device__ __forceinline__ float fq_sum(float x) { float a = x, b = x; pl16(a, b); float y = a + b, c = y; pl32(y, c); return y + c; }
; __device__ __forceinline__ void phase_attn_a(const bf16_t* Qb, const bf16_t* Kb, const bf16_t* Vt, bf16_t* O, const float* lam, const float* subg, const float* qg, const float* kg, float lam_init, LAS unsigned char* lds, int wv) {
;     ...
;             for (int qb = 0; qb < 2; ++qb) { float ss = 0.f;
; #pragma unroll
;                 for (int db = 0; db < 8; ++db) { const f32x4 o1 = xb[(g * 16 + db * 2 + qb) * 64 + lane]; const f32x4 v = oacc[db][qb] - lam_full * o1; oacc[db][qb] = v;
;                     ss += (v[0] * v[0] + v[1] * v[1]) + (v[2] * v[2] + v[3] * v[3]); }
;                 ss = fq_sum(ss);
;                 const float rinv = rsqrtf(ss * (1.0f / 128.0f) + 1e-5f) * (1.0f - lam_init);
;                 bf16_t* rp = O + (size_t)(b * T + q0 + qb * 16 + cfr) * 1024 + hh * 128 + 8 * cfq;
; #pragma unroll
;                 for (int e = 0; e < 4; ++e) {
;                     const f32x4 g0 = *(const f32x4*)(subg + e * 32 + 8 * cfq), g1 = *(const f32x4*)(subg + e * 32 + 8 * cfq + 4);
;                     const f32x4 v0 = oacc[2 * e][qb] * rinv * g0, v1 = oacc[2 * e + 1][qb] * rinv * g1;
;                     u32x4 w; w.x = cvt_pk_bf16(v0[0], v0[1]); w.y = cvt_pk_bf16(v0[2], v0[3]); w.z = cvt_pk_bf16(v1[0], v1[1]); w.w = cvt_pk_bf16(v1[2], v1[3]); *(u32x4*)(rp + e * 32) = w; } }
	v_pk_fma_f32 v[22:23], s[38:39], v[14:15], v[6:7]
	v_pk_fma_f32 v[24:25], s[20:21], v[12:13], v[4:5] neg_lo:[1,0,0] neg_hi:[1,0,0]
	v_pk_mul_f32 v[6:7], v[22:23], v[22:23]
	v_pk_mul_f32 v[4:5], v[24:25], v[24:25]
	s_nop 0
	v_pk_mov_b32 v[12:13], v[4:5], v[6:7] op_sel:[1,0]
	v_mov_b32_e32 v5, v7
	v_pk_add_f32 v[26:27], v[12:13], v[4:5]
	ds_read_b128 v[4:7], v236 offset:13312
	s_waitcnt lgkmcnt(0)
	v_pk_fma_f32 v[12:13], s[38:39], v[6:7], v[2:3]
	v_pk_fma_f32 v[14:15], s[20:21], v[4:5], v[0:1] neg_lo:[1,0,0] neg_hi:[1,0,0]
	ds_read_b128 v[0:3], v236 offset:15360
	s_waitcnt lgkmcnt(0)
	v_pk_fma_f32 v[8:9], s[20:21], v[0:1], v[8:9] neg_lo:[1,0,0] neg_hi:[1,0,0]
	v_pk_fma_f32 v[10:11], s[38:39], v[2:3], v[10:11]
	v_mul_f32_e32 v2, v8, v8
	v_pk_add_f32 v[0:1], v[16:17], v[16:17] op_sel:[0,1] op_sel_hi:[1,0]
	v_mul_f32_e32 v4, v9, v9
	v_mov_b32_e32 v1, v2
	v_pk_add_f32 v[2:3], v[26:27], v[26:27] op_sel:[0,1] op_sel_hi:[1,0]
	v_mul_f32_e32 v5, v10, v10
	v_mov_b32_e32 v3, v4
	v_pk_add_f32 v[0:1], v[0:1], v[2:3]
	v_mul_f32_e32 v2, v15, v15
	v_pk_fma_f32 v[2:3], v[14:15], v[14:15], v[2:3] op_sel_hi:[1,1,0]
	v_mul_f32_e32 v4, v13, v13
	v_mul_f32_e32 v6, v11, v11
	v_mov_b32_e32 v3, v5
	v_pk_fma_f32 v[4:5], v[12:13], v[12:13], v[4:5] op_sel_hi:[1,1,0]
	s_nop 0
	v_mov_b32_e32 v5, v6
	v_pk_add_f32 v[2:3], v[2:3], v[4:5]
	s_nop 0
	v_pk_add_f32 v[0:1], v[0:1], v[2:3]
	s_nop 0
	v_add_f32_e32 v0, v0, v1
	v_mov_b32_e32 v1, v0
	s_nop 1
	v_permlane16_swap_b32 v1, v0
	s_nop 0
	v_add_f32_e32 v0, v1, v0
	v_mov_b32_e32 v1, v0
	s_nop 1
	v_permlane32_swap_b32 v1, v0
	s_nop 0
	v_add_f32_e32 v0, v1, v0
	v_fmamk_f32 v0, v0, 0x3c000000, v51
	v_cmp_gt_f32_e32 vcc, s2, v0
	v_mul_f32_e32 v1, 0x4b800000, v0
	s_nop 0
	v_cndmask_b32_e32 v0, v0, v1, vcc
	v_rsq_f32_e32 v0, v0
	s_nop 0
	v_mul_f32_e32 v1, 0x45800000, v0
	v_cndmask_b32_e32 v0, v0, v1, vcc
	v_mul_f32_e32 v16, v234, v0
	v_add_u32_e32 v0, 16, v66
	v_ashrrev_i32_e32 v1, 31, v0
	v_lshlrev_b64 v[0:1], 11, v[0:1]
	v_lshl_add_u64 v[26:27], v[68:69], 0, v[0:1]
	global_load_dwordx4 v[0:3], v[64:65], off offset:16
	global_load_dwordx4 v[4:7], v[64:65], off
	v_pk_mul_f32 v[38:39], v[38:39], v[16:17] op_sel_hi:[1,0]
	v_pk_mul_f32 v[36:37], v[36:37], v[16:17] op_sel_hi:[1,0]
	v_pk_mul_f32 v[42:43], v[42:43], v[16:17] op_sel_hi:[1,0]
	v_pk_mul_f32 v[40:41], v[40:41], v[16:17] op_sel_hi:[1,0]
	v_pk_mul_f32 v[30:31], v[30:31], v[16:17] op_sel_hi:[1,0]
	v_pk_mul_f32 v[28:29], v[28:29], v[16:17] op_sel_hi:[1,0]
	v_pk_mul_f32 v[34:35], v[34:35], v[16:17] op_sel_hi:[1,0]
	v_pk_mul_f32 v[32:33], v[32:33], v[16:17] op_sel_hi:[1,0]
	v_pk_mul_f32 v[20:21], v[20:21], v[16:17] op_sel_hi:[1,0]
	v_pk_mul_f32 v[18:19], v[18:19], v[16:17] op_sel_hi:[1,0]
	v_pk_mul_f32 v[8:9], v[8:9], v[16:17] op_sel_hi:[1,0]
	v_pk_mul_f32 v[10:11], v[10:11], v[16:17] op_sel_hi:[1,0]
	v_pk_mul_f32 v[14:15], v[14:15], v[16:17] op_sel_hi:[1,0]
	v_pk_mul_f32 v[12:13], v[12:13], v[16:17] op_sel_hi:[1,0]
	s_waitcnt vmcnt(0)
	v_pk_mul_f32 v[36:37], v[2:3], v[36:37]
	v_pk_mul_f32 v[2:3], v[0:1], v[38:39]
	v_pk_mul_f32 v[6:7], v[6:7], v[40:41]
	v_pk_mul_f32 v[4:5], v[4:5], v[42:43]
	s_nop 0
	v_cvt_pk_bf16_f32 v0, v4, v5
	v_cvt_pk_bf16_f32 v1, v6, v7
	v_cvt_pk_bf16_f32 v2, v2, v3
	v_cvt_pk_bf16_f32 v3, v36, v37
	global_store_dwordx4 v[26:27], v[0:3], off
	global_load_dwordx4 v[0:3], v[64:65], off offset:144
	s_nop 0
	global_load_dwordx4 v[4:7], v[64:65], off offset:128
	s_waitcnt vmcnt(0)
	v_pk_mul_f32 v[28:29], v[2:3], v[28:29]
	v_pk_mul_f32 v[2:3], v[0:1], v[30:31]
	v_pk_mul_f32 v[6:7], v[6:7], v[32:33]
	v_pk_mul_f32 v[4:5], v[4:5], v[34:35]
	s_nop 0
	v_cvt_pk_bf16_f32 v0, v4, v5
	v_cvt_pk_bf16_f32 v1, v6, v7
	v_cvt_pk_bf16_f32 v2, v2, v3
	v_cvt_pk_bf16_f32 v3, v28, v29
	global_store_dwordx4 v[26:27], v[0:3], off offset:64
	global_load_dwordx4 v[0:3], v[64:65], off offset:272
	s_nop 0
	global_load_dwordx4 v[4:7], v[64:65], off offset:256
	s_waitcnt vmcnt(0)
	v_pk_mul_f32 v[6:7], v[18:19], v[6:7]
	v_pk_mul_f32 v[4:5], v[20:21], v[4:5]
	v_pk_mul_f32 v[18:19], v[24:25], v[16:17] op_sel_hi:[1,0]
	v_pk_mul_f32 v[20:21], v[22:23], v[16:17] op_sel_hi:[1,0]
	s_nop 0
	v_pk_mul_f32 v[20:21], v[20:21], v[2:3]
	v_pk_mul_f32 v[2:3], v[18:19], v[0:1]
	v_cvt_pk_bf16_f32 v0, v4, v5
	v_cvt_pk_bf16_f32 v1, v6, v7
	s_nop 0
	v_cvt_pk_bf16_f32 v2, v2, v3
	v_cvt_pk_bf16_f32 v3, v20, v21
	global_store_dwordx4 v[26:27], v[0:3], off offset:128
	global_load_dwordx4 v[0:3], v[64:65], off offset:400
	s_nop 0
	global_load_dwordx4 v[4:7], v[64:65], off offset:384
	s_waitcnt vmcnt(0)
	v_pk_mul_f32 v[10:11], v[10:11], v[2:3]
	v_pk_mul_f32 v[2:3], v[8:9], v[0:1]
	v_pk_mul_f32 v[6:7], v[12:13], v[6:7]
	v_pk_mul_f32 v[4:5], v[14:15], v[4:5]
	s_nop 0
	v_cvt_pk_bf16_f32 v0, v4, v5
	v_cvt_pk_bf16_f32 v1, v6, v7
	v_cvt_pk_bf16_f32 v2, v2, v3
	v_cvt_pk_bf16_f32 v3, v10, v11
	global_store_dwordx4 v[26:27], v[0:3], off offset:192
	s_branch .LBB0_1951

; #define G_STAGE(bufoff, gbase, voff) do { _Pragma("unroll") for (int _i = 0; _i < 2; ++_i) \
;     __builtin_amdgcn_global_load_lds((const unsigned*)((const char*)(gbase) + (voff)[_i]), (LAS unsigned*)(lds + (bufoff) + ldsw + _i * 8192), 16, 0, 0); } while (0)
; #define G_LDA(dst, b, h) do { _Pragma("unroll") for (int m = 0; m < 4; ++m) _Pragma("unroll") for (int k = 0; k < 2; ++k) dst[m][k] = *(const LAS bf16x8*)(lds + G_SA(b, h) + aoff + m * 2048 + k * 1024); } while (0)
; #define G_LDB(dst, b, h) do { _Pragma("unroll") for (int n = 0; n < 2; ++n) _Pragma("unroll") for (int k = 0; k < 2; ++k) dst[n][k] = *(const LAS bf16x8*)(lds + G_SB(b, h) + boff + n * 2048 + k * 1024); } while (0)
; #define WAIT_V(n) asm volatile("s_waitcnt vmcnt(" #n ")" ::: "memory")
; #define WAIT_L(n) asm volatile("s_waitcnt lgkmcnt(" #n ")" ::: "memory")
; #define BAR __builtin_amdgcn_s_barrier()
; #define SCHED __builtin_amdgcn_sched_barrier(0)
; template <class Epi>
; __device__ __forceinline__ void gemm_phase(const bf16_t* __restrict__ A, int lda, const bf16_t* __restrict__ Bt, int ldb, int K, int nM, int nN, const Epi& epi, LAS unsigned char* lds, int wv) {
;     ...
;         for (int t = 0; t < nt; t += 2) {
;             const bool last = (t == nt - 2);
;             const char* a1 = cA + (size_t)(t + 1) * kstep;
;             const char* a2 = last ? nA : cA + (size_t)(t + 2) * kstep; const char* b2 = last ? nB : cB + (size_t)(t + 2) * kstep;
;             const char* a3 = a2 + kstep; const char* b3 = b2 + kstep;
;             G_LDB(B0, 0, 0); G_LDB(B1, 0, 1); SCHED; G_LDA(At, 0, 0); G_STAGE(G_SA(1, 1), a1 + hstep, voffA);
;             WAIT_V(8); WAIT_L(0); BAR; G_MMA(0, 0, At, B0); G_MMA(0, 1, At, B1); BAR; SCHED;
;             G_LDA(At, 0, 1); G_STAGE(G_SB(0, 0), b2, voffA); G_STAGE(G_SB(0, 1), b2 + hstep, voffA); G_STAGE(G_SA(0, 0), a2, voffA);
;             WAIT_V(8); WAIT_L(0); BAR; G_MMA(1, 0, At, B0); G_MMA(1, 1, At, B1); BAR; SCHED;
;             G_LDB(B0, 1, 0); G_LDB(B1, 1, 1); SCHED; G_LDA(At, 1, 0); G_STAGE(G_SA(0, 1), a2 + hstep, voffA);
;             WAIT_V(8); WAIT_L(0); BAR; G_MMA(0, 0, At, B0); G_MMA(0, 1, At, B1); BAR; SCHED;
;             G_LDA(At, 1, 1); G_STAGE(G_SB(1, 0), b3, voffA); G_STAGE(G_SB(1, 1), b3 + hstep, voffA); G_STAGE(G_SA(1, 0), a3, voffA);
;             WAIT_V(8); WAIT_L(0); BAR; G_MMA(1, 0, At, B0); G_MMA(1, 1, At, B1); BAR; SCHED;
.LBB0_2017:
	s_add_u32 s40, s38, 0x100
	s_addc_u32 s41, s39, 0
	s_add_i32 s58, 0, 0x10000
	s_cmp_eq_u32 s57, 12
	s_cselect_b32 s45, s31, s41
	s_cselect_b32 s44, s30, s40
	v_add_u32_e32 v138, s58, v142
	s_cselect_b32 s43, s9, s23
	s_cselect_b32 s42, s8, s21
	s_add_i32 s59, 0, 0x14000
	ds_read_b128 v[134:137], v138
	ds_read_b128 v[144:147], v138 offset:1024
	ds_read_b128 v[148:151], v138 offset:2048
	ds_read_b128 v[152:155], v138 offset:3072
	v_add_u32_e32 v138, s59, v142
	ds_read_b128 v[156:159], v138
	ds_read_b128 v[160:163], v138 offset:1024
	ds_read_b128 v[164:167], v138 offset:2048
	ds_read_b128 v[168:171], v138 offset:3072
	v_lshl_add_u64 v[138:139], s[38:39], 0, v[132:133]
	s_add_i32 m0, s49, 0xc000
	ds_read_b128 v[172:175], v143
	ds_read_b128 v[176:179], v143 offset:1024
	ds_read_b128 v[180:183], v143 offset:2048
	ds_read_b128 v[184:187], v143 offset:3072
	ds_read_b128 v[188:191], v143 offset:4096
	ds_read_b128 v[194:197], v143 offset:5120
	ds_read_b128 v[198:201], v143 offset:6144
	ds_read_b128 v[202:205], v143 offset:7168
	global_load_lds_dwordx4 v[138:139], off
	v_lshl_add_u64 v[138:139], s[38:39], 0, v[130:131]
	s_add_i32 m0, s49, 0xe000
	s_nop 0
	global_load_lds_dwordx4 v[138:139], off
	s_waitcnt vmcnt(8)
	s_waitcnt lgkmcnt(0)
	s_barrier
	s_setprio 1
	s_waitcnt lgkmcnt(0)
	v_mfma_f32_16x16x32_bf16 v[124:127], v[134:137], v[172:175], v[124:127]
	v_mfma_f32_16x16x32_bf16 v[120:123], v[148:151], v[172:175], v[120:123]
	v_mfma_f32_16x16x32_bf16 v[108:111], v[134:137], v[180:183], v[108:111]
	v_mfma_f32_16x16x32_bf16 v[104:107], v[148:151], v[180:183], v[104:107]
	v_mfma_f32_16x16x32_bf16 v[92:95], v[134:137], v[188:191], v[92:95]
	v_mfma_f32_16x16x32_bf16 v[88:91], v[148:151], v[188:191], v[88:91]
	v_mfma_f32_16x16x32_bf16 v[76:79], v[134:137], v[198:201], v[76:79]
	v_mfma_f32_16x16x32_bf16 v[72:75], v[148:151], v[198:201], v[72:75]
	v_mfma_f32_16x16x32_bf16 v[124:127], v[144:147], v[176:179], v[124:127]
	v_mfma_f32_16x16x32_bf16 v[120:123], v[152:155], v[176:179], v[120:123]
	v_mfma_f32_16x16x32_bf16 v[108:111], v[144:147], v[184:187], v[108:111]
	v_mfma_f32_16x16x32_bf16 v[104:107], v[152:155], v[184:187], v[104:107]
	v_mfma_f32_16x16x32_bf16 v[92:95], v[144:147], v[194:197], v[92:95]
	v_mfma_f32_16x16x32_bf16 v[88:91], v[152:155], v[194:197], v[88:91]
	v_mfma_f32_16x16x32_bf16 v[76:79], v[144:147], v[202:205], v[76:79]
	v_mfma_f32_16x16x32_bf16 v[72:75], v[152:155], v[202:205], v[72:75]
	s_setprio 0
	s_setprio 1
	v_mfma_f32_16x16x32_bf16 v[116:119], v[156:159], v[172:175], v[116:119]
	v_mfma_f32_16x16x32_bf16 v[112:115], v[164:167], v[172:175], v[112:115]
	v_mfma_f32_16x16x32_bf16 v[100:103], v[156:159], v[180:183], v[100:103]
	v_mfma_f32_16x16x32_bf16 v[96:99], v[164:167], v[180:183], v[96:99]
	v_mfma_f32_16x16x32_bf16 v[84:87], v[156:159], v[188:191], v[84:87]
	v_mfma_f32_16x16x32_bf16 v[80:83], v[164:167], v[188:191], v[80:83]
	v_mfma_f32_16x16x32_bf16 v[68:71], v[156:159], v[198:201], v[68:71]
	v_mfma_f32_16x16x32_bf16 v[64:67], v[164:167], v[198:201], v[64:67]
	v_mfma_f32_16x16x32_bf16 v[116:119], v[160:163], v[176:179], v[116:119]
	v_mfma_f32_16x16x32_bf16 v[112:115], v[168:171], v[176:179], v[112:115]
	v_mfma_f32_16x16x32_bf16 v[100:103], v[160:163], v[184:187], v[100:103]
	v_mfma_f32_16x16x32_bf16 v[96:99], v[168:171], v[184:187], v[96:99]
	v_mfma_f32_16x16x32_bf16 v[84:87], v[160:163], v[194:197], v[84:87]
	v_mfma_f32_16x16x32_bf16 v[80:83], v[168:171], v[194:197], v[80:83]
	v_mfma_f32_16x16x32_bf16 v[68:71], v[160:163], v[202:205], v[68:71]
	v_mfma_f32_16x16x32_bf16 v[64:67], v[168:171], v[202:205], v[64:67]
	s_setprio 0
	s_barrier
	s_add_i32 s38, s58, s33
	v_lshl_add_u64 v[138:139], s[42:43], 0, v[192:193]
	s_mov_b32 m0, s38
	ds_read_b128 v[172:175], v143 offset:16384
	ds_read_b128 v[176:179], v143 offset:17408
	ds_read_b128 v[180:183], v143 offset:18432
	ds_read_b128 v[184:187], v143 offset:19456
	ds_read_b128 v[188:191], v143 offset:20480
	ds_read_b128 v[194:197], v143 offset:21504
	ds_read_b128 v[198:201], v143 offset:22528
	ds_read_b128 v[202:205], v143 offset:23552
	global_load_lds_dwordx4 v[138:139], off
	s_add_i32 m0, s38, 0x2000
	s_add_u32 s38, s42, 0x40000
	v_lshl_add_u64 v[206:207], s[42:43], 0, v[128:129]
	s_addc_u32 s39, s43, 0
	s_add_i32 s58, s59, s33
	global_load_lds_dwordx4 v[206:207], off
	v_lshl_add_u64 v[208:209], s[38:39], 0, v[192:193]
	s_mov_b32 m0, s58
	v_lshl_add_u64 v[210:211], s[44:45], 0, v[128:129]
	global_load_lds_dwordx4 v[208:209], off
	v_lshl_add_u64 v[208:209], s[38:39], 0, v[128:129]
	s_add_i32 m0, s58, 0x2000
	s_nop 0
	global_load_lds_dwordx4 v[208:209], off
	v_lshl_add_u64 v[208:209], s[44:45], 0, v[192:193]
	s_mov_b32 m0, s49
	s_nop 0
	global_load_lds_dwordx4 v[208:209], off
	s_mov_b32 m0, s37
	s_nop 0
	global_load_lds_dwordx4 v[210:211], off
	s_waitcnt vmcnt(8)
	s_waitcnt lgkmcnt(0)
	s_barrier
; #define G_STAGE(bufoff, gbase, voff) do { _Pragma("unroll") for (int _i = 0; _i < 2; ++_i) \
;     __builtin_amdgcn_global_load_lds((const unsigned*)((const char*)(gbase) + (voff)[_i]), (LAS unsigned*)(lds + (bufoff) + ldsw + _i * 8192), 16, 0, 0); } while (0)
; #define G_LDA(dst, b, h) do { _Pragma("unroll") for (int m = 0; m < 4; ++m) _Pragma("unroll") for (int k = 0; k < 2; ++k) dst[m][k] = *(const LAS bf16x8*)(lds + G_SA(b, h) + aoff + m * 2048 + k * 1024); } while (0)
; #define G_LDB(dst, b, h) do { _Pragma("unroll") for (int n = 0; n < 2; ++n) _Pragma("unroll") for (int k = 0; k < 2; ++k) dst[n][k] = *(const LAS bf16x8*)(lds + G_SB(b, h) + boff + n * 2048 + k * 1024); } while (0)
; #define G_MMA(ai, bj, At, Bt) do { __builtin_amdgcn_s_setprio(1); _Pragma("unroll") for (int m = 0; m < 4; ++m) _Pragma("unroll") for (int n = 0; n < 2; ++n) _Pragma("unroll") for (int k = 0; k < 2; ++k) \
;     acc[ai][bj][m][n] = __builtin_amdgcn_mfma_f32_16x16x32_bf16(Bt[n][k], At[m][k], acc[ai][bj][m][n], 0, 0, 0); __builtin_amdgcn_s_setprio(0); } while (0)
; #define WAIT_V(n) asm volatile("s_waitcnt vmcnt(" #n ")" ::: "memory")
; #define WAIT_L(n) asm volatile("s_waitcnt lgkmcnt(" #n ")" ::: "memory")
; #define BAR __builtin_amdgcn_s_barrier()
; #define SCHED __builtin_amdgcn_sched_barrier(0)
; template <class Epi>
; __device__ __forceinline__ void gemm_phase(const bf16_t* __restrict__ A, int lda, const bf16_t* __restrict__ Bt, int ldb, int K, int nM, int nN, const Epi& epi, LAS unsigned char* lds, int wv) {
;     ...
;             G_LDB(B0, 0, 0); G_LDB(B1, 0, 1); SCHED; G_LDA(At, 0, 0); G_STAGE(G_SA(1, 1), a1 + hstep, voffA);
;             WAIT_V(8); WAIT_L(0); BAR; G_MMA(0, 0, At, B0); G_MMA(0, 1, At, B1); BAR; SCHED;
;             G_LDA(At, 0, 1); G_STAGE(G_SB(0, 0), b2, voffA); G_STAGE(G_SB(0, 1), b2 + hstep, voffA); G_STAGE(G_SA(0, 0), a2, voffA);
;             WAIT_V(8); WAIT_L(0); BAR; G_MMA(1, 0, At, B0); G_MMA(1, 1, At, B1); BAR; SCHED;
;             G_LDB(B0, 1, 0); G_LDB(B1, 1, 1); SCHED; G_LDA(At, 1, 0); G_STAGE(G_SA(0, 1), a2 + hstep, voffA);
;             WAIT_V(8); WAIT_L(0); BAR; G_MMA(0, 0, At, B0); G_MMA(0, 1, At, B1); BAR; SCHED;
;             G_LDA(At, 1, 1); G_STAGE(G_SB(1, 0), b3, voffA); G_STAGE(G_SB(1, 1), b3 + hstep, voffA); G_STAGE(G_SA(1, 0), a3, voffA);
;             WAIT_V(8); WAIT_L(0); BAR; G_MMA(1, 0, At, B0); G_MMA(1, 1, At, B1); BAR; SCHED;
	s_setprio 1
	s_waitcnt lgkmcnt(0)
	v_mfma_f32_16x16x32_bf16 v[60:63], v[134:137], v[172:175], v[60:63]
	v_mfma_f32_16x16x32_bf16 v[56:59], v[148:151], v[172:175], v[56:59]
	v_mfma_f32_16x16x32_bf16 v[44:47], v[134:137], v[180:183], v[44:47]
	v_mfma_f32_16x16x32_bf16 v[40:43], v[148:151], v[180:183], v[40:43]
	v_mfma_f32_16x16x32_bf16 v[28:31], v[134:137], v[188:191], v[28:31]
	v_mfma_f32_16x16x32_bf16 v[24:27], v[148:151], v[188:191], v[24:27]
	v_mfma_f32_16x16x32_bf16 v[12:15], v[134:137], v[198:201], v[12:15]
	v_mfma_f32_16x16x32_bf16 v[8:11], v[148:151], v[198:201], v[8:11]
	v_mfma_f32_16x16x32_bf16 v[60:63], v[144:147], v[176:179], v[60:63]
	v_mfma_f32_16x16x32_bf16 v[56:59], v[152:155], v[176:179], v[56:59]
	v_mfma_f32_16x16x32_bf16 v[44:47], v[144:147], v[184:187], v[44:47]
	v_mfma_f32_16x16x32_bf16 v[40:43], v[152:155], v[184:187], v[40:43]
	v_mfma_f32_16x16x32_bf16 v[28:31], v[144:147], v[194:197], v[28:31]
	v_mfma_f32_16x16x32_bf16 v[24:27], v[152:155], v[194:197], v[24:27]
	v_mfma_f32_16x16x32_bf16 v[12:15], v[144:147], v[202:205], v[12:15]
	v_mfma_f32_16x16x32_bf16 v[8:11], v[152:155], v[202:205], v[8:11]
	s_setprio 0
	s_setprio 1
	v_mfma_f32_16x16x32_bf16 v[52:55], v[156:159], v[172:175], v[52:55]
	v_mfma_f32_16x16x32_bf16 v[48:51], v[164:167], v[172:175], v[48:51]
	v_mfma_f32_16x16x32_bf16 v[36:39], v[156:159], v[180:183], v[36:39]
	v_mfma_f32_16x16x32_bf16 v[32:35], v[164:167], v[180:183], v[32:35]
	v_mfma_f32_16x16x32_bf16 v[20:23], v[156:159], v[188:191], v[20:23]
	v_mfma_f32_16x16x32_bf16 v[16:19], v[164:167], v[188:191], v[16:19]
	v_mfma_f32_16x16x32_bf16 v[4:7], v[156:159], v[198:201], v[4:7]
	v_mfma_f32_16x16x32_bf16 v[0:3], v[164:167], v[198:201], v[0:3]
	v_mfma_f32_16x16x32_bf16 v[52:55], v[160:163], v[176:179], v[52:55]
	v_mfma_f32_16x16x32_bf16 v[48:51], v[168:171], v[176:179], v[48:51]
	v_mfma_f32_16x16x32_bf16 v[36:39], v[160:163], v[184:187], v[36:39]
	v_mfma_f32_16x16x32_bf16 v[32:35], v[168:171], v[184:187], v[32:35]
	v_mfma_f32_16x16x32_bf16 v[20:23], v[160:163], v[194:197], v[20:23]
	v_mfma_f32_16x16x32_bf16 v[16:19], v[168:171], v[194:197], v[16:19]
	v_mfma_f32_16x16x32_bf16 v[4:7], v[160:163], v[202:205], v[4:7]
	v_mfma_f32_16x16x32_bf16 v[0:3], v[168:171], v[202:205], v[0:3]
	s_setprio 0
	s_barrier
	s_add_i32 s58, 0, 0x18000
	s_add_i32 s59, 0, 0x1c000
	v_add_u32_e32 v152, s58, v142
	v_add_u32_e32 v168, s59, v142
	ds_read_b128 v[134:137], v152
	ds_read_b128 v[144:147], v152 offset:1024
	ds_read_b128 v[148:151], v152 offset:2048
	ds_read_b128 v[152:155], v152 offset:3072
	ds_read_b128 v[156:159], v168
	ds_read_b128 v[160:163], v168 offset:1024
	ds_read_b128 v[164:167], v168 offset:2048
	ds_read_b128 v[168:171], v168 offset:3072
	s_add_u32 s38, s44, 0x40000
	s_addc_u32 s39, s45, 0
	s_mov_b32 m0, s50
	v_lshl_add_u64 v[212:213], s[38:39], 0, v[192:193]
	ds_read_b128 v[172:175], v143 offset:32768
	ds_read_b128 v[176:179], v143 offset:33792
	ds_read_b128 v[180:183], v143 offset:34816
	ds_read_b128 v[184:187], v143 offset:35840
	ds_read_b128 v[188:191], v143 offset:36864
	ds_read_b128 v[194:197], v143 offset:37888
	ds_read_b128 v[198:201], v143 offset:38912
	ds_read_b128 v[202:205], v143 offset:39936
	global_load_lds_dwordx4 v[212:213], off
	v_lshl_add_u64 v[212:213], s[38:39], 0, v[128:129]
	s_mov_b32 m0, s51
	s_nop 0
	global_load_lds_dwordx4 v[212:213], off
	s_waitcnt vmcnt(8)
	s_waitcnt lgkmcnt(0)
	s_barrier
	s_setprio 1
	s_waitcnt lgkmcnt(0)
	v_mfma_f32_16x16x32_bf16 v[124:127], v[134:137], v[172:175], v[124:127]
	v_mfma_f32_16x16x32_bf16 v[120:123], v[148:151], v[172:175], v[120:123]
	v_mfma_f32_16x16x32_bf16 v[108:111], v[134:137], v[180:183], v[108:111]
	v_mfma_f32_16x16x32_bf16 v[104:107], v[148:151], v[180:183], v[104:107]
	v_mfma_f32_16x16x32_bf16 v[92:95], v[134:137], v[188:191], v[92:95]
	v_mfma_f32_16x16x32_bf16 v[88:91], v[148:151], v[188:191], v[88:91]
	v_mfma_f32_16x16x32_bf16 v[76:79], v[134:137], v[198:201], v[76:79]
	v_mfma_f32_16x16x32_bf16 v[72:75], v[148:151], v[198:201], v[72:75]
	v_mfma_f32_16x16x32_bf16 v[124:127], v[144:147], v[176:179], v[124:127]
	v_mfma_f32_16x16x32_bf16 v[120:123], v[152:155], v[176:179], v[120:123]
	v_mfma_f32_16x16x32_bf16 v[108:111], v[144:147], v[184:187], v[108:111]
	v_mfma_f32_16x16x32_bf16 v[104:107], v[152:155], v[184:187], v[104:107]
	v_mfma_f32_16x16x32_bf16 v[92:95], v[144:147], v[194:197], v[92:95]
	v_mfma_f32_16x16x32_bf16 v[88:91], v[152:155], v[194:197], v[88:91]
	v_mfma_f32_16x16x32_bf16 v[76:79], v[144:147], v[202:205], v[76:79]
	v_mfma_f32_16x16x32_bf16 v[72:75], v[152:155], v[202:205], v[72:75]
	s_setprio 0
	s_setprio 1
	v_mfma_f32_16x16x32_bf16 v[116:119], v[156:159], v[172:175], v[116:119]
	v_mfma_f32_16x16x32_bf16 v[112:115], v[164:167], v[172:175], v[112:115]
	v_mfma_f32_16x16x32_bf16 v[100:103], v[156:159], v[180:183], v[100:103]
	v_mfma_f32_16x16x32_bf16 v[96:99], v[164:167], v[180:183], v[96:99]
	v_mfma_f32_16x16x32_bf16 v[84:87], v[156:159], v[188:191], v[84:87]
	v_mfma_f32_16x16x32_bf16 v[80:83], v[164:167], v[188:191], v[80:83]
	v_mfma_f32_16x16x32_bf16 v[68:71], v[156:159], v[198:201], v[68:71]
	v_mfma_f32_16x16x32_bf16 v[64:67], v[164:167], v[198:201], v[64:67]
	v_mfma_f32_16x16x32_bf16 v[116:119], v[160:163], v[176:179], v[116:119]
	v_mfma_f32_16x16x32_bf16 v[112:115], v[168:171], v[176:179], v[112:115]
	v_mfma_f32_16x16x32_bf16 v[100:103], v[160:163], v[184:187], v[100:103]
	v_mfma_f32_16x16x32_bf16 v[96:99], v[168:171], v[184:187], v[96:99]
	v_mfma_f32_16x16x32_bf16 v[84:87], v[160:163], v[194:197], v[84:87]
	v_mfma_f32_16x16x32_bf16 v[80:83], v[168:171], v[194:197], v[80:83]
	v_mfma_f32_16x16x32_bf16 v[68:71], v[160:163], v[202:205], v[68:71]
	v_mfma_f32_16x16x32_bf16 v[64:67], v[168:171], v[202:205], v[64:67]
	s_setprio 0
	s_barrier
; #define G_STAGE(bufoff, gbase, voff) do { _Pragma("unroll") for (int _i = 0; _i < 2; ++_i) \
;     __builtin_amdgcn_global_load_lds((const unsigned*)((const char*)(gbase) + (voff)[_i]), (LAS unsigned*)(lds + (bufoff) + ldsw + _i * 8192), 16, 0, 0); } while (0)
; #define BAR __builtin_amdgcn_s_barrier()
; template <class Epi>
; __device__ __forceinline__ void gemm_phase(const bf16_t* __restrict__ A, int lda, const bf16_t* __restrict__ Bt, int ldb, int K, int nM, int nN, const Epi& epi, LAS unsigned char* lds, int wv) {
;     ...
;             WAIT_V(8); WAIT_L(0); BAR; G_MMA(0, 0, At, B0); G_MMA(0, 1, At, B1); BAR; SCHED;
;             G_LDA(At, 1, 1); G_STAGE(G_SB(1, 0), b3, voffA); G_STAGE(G_SB(1, 1), b3 + hstep, voffA); G_STAGE(G_SA(1, 0), a3, voffA);
;             WAIT_V(8); WAIT_L(0); BAR; G_MMA(1, 0, At, B0); G_MMA(1, 1, At, B1); BAR; SCHED;
;         }
;         { int efr = fr, efq = fq; asm volatile("" : "+v"(efr), "+v"(efq));
;           epi(acc, pm, pn, wr, wc, efr, efq); }
;     __device__ __forceinline__ void operator()(AccRef acc, int pm, int pn, int wr, int wc, int fr, int fq) const {
;     ...
;             for (int m = 0; m < 4; ++m) { const int row = EPI_ROW(ai, m); const float* gp = gate + (size_t)(row >> 12) * 9216; const size_t ro = (size_t)row * 1024;
; #pragma unroll
;                 for (int bj = 0; bj < 2; ++bj) { const int col = pn * 256 + wc * 64 + bj * 32 + 8 * fq;
;                     const f32x4 g0 = *(const f32x4*)(gp + col), g1 = *(const f32x4*)(gp + col + 4);
;                     f32x4 x0, x1;
;                     if (mode == 0) { x0 = *(const f32x4*)(xin_f + ro + col); x1 = *(const f32x4*)(xin_f + ro + col + 4); }
;                     else { const h16x8 h = *(const h16x8*)(xh + ro + col); x0 = (f32x4){(float)h[0], (float)h[1], (float)h[2], (float)h[3]}; x1 = (f32x4){(float)h[4], (float)h[5], (float)h[6], (float)h[7]}; }
;                     const f32x4 y0 = x0 + gs * g0 * acc[ai][bj][m][0], y1 = x1 + gs * g1 * acc[ai][bj][m][1];
;                     if (mode == 2) { *(f32x4*)(xout_f + ro + col) = y0; *(f32x4*)(xout_f + ro + col + 4) = y1; }
;                     else { h16x8 h; h[0] = (_Float16)y0[0]; h[1] = (_Float16)y0[1]; h[2] = (_Float16)y0[2]; h[3] = (_Float16)y0[3]; h[4] = (_Float16)y1[0]; h[5] = (_Float16)y1[1]; h[6] = (_Float16)y1[2]; h[7] = (_Float16)y1[3];
;                         *(h16x8*)(xh + ro + col) = h; } } }
	s_add_i32 s38, s58, s33
	v_lshl_add_u64 v[138:139], v[138:139], 0, s[10:11]
	s_mov_b32 m0, s38
	ds_read_b128 v[172:175], v143 offset:49152
	ds_read_b128 v[176:179], v143 offset:50176
	ds_read_b128 v[180:183], v143 offset:51200
	ds_read_b128 v[184:187], v143 offset:52224
	ds_read_b128 v[188:191], v143 offset:53248
	ds_read_b128 v[194:197], v143 offset:54272
	ds_read_b128 v[198:201], v143 offset:55296
	ds_read_b128 v[202:205], v143 offset:56320
	global_load_lds_dwordx4 v[138:139], off
	s_add_i32 m0, s38, 0x2000
	s_add_u32 s38, s42, 0x40080
	v_lshl_add_u64 v[138:139], v[206:207], 0, s[10:11]
	s_addc_u32 s39, s43, 0
	s_add_i32 s42, s59, s33
	global_load_lds_dwordx4 v[138:139], off
	v_lshl_add_u64 v[138:139], s[38:39], 0, v[192:193]
	s_mov_b32 m0, s42
	s_nop 0
	global_load_lds_dwordx4 v[138:139], off
	v_lshl_add_u64 v[138:139], s[38:39], 0, v[128:129]
	s_add_i32 m0, s42, 0x2000
	s_nop 0
	global_load_lds_dwordx4 v[138:139], off
	v_lshl_add_u64 v[138:139], v[208:209], 0, s[10:11]
	s_mov_b32 m0, s4
	s_nop 0
	global_load_lds_dwordx4 v[138:139], off
	v_lshl_add_u64 v[138:139], v[210:211], 0, s[10:11]
	s_mov_b32 m0, s52
	s_nop 0
	global_load_lds_dwordx4 v[138:139], off
	s_waitcnt vmcnt(8)
	s_waitcnt lgkmcnt(0)
	s_barrier
	s_setprio 1
	s_waitcnt lgkmcnt(0)
	v_mfma_f32_16x16x32_bf16 v[60:63], v[134:137], v[172:175], v[60:63]
	v_mfma_f32_16x16x32_bf16 v[56:59], v[148:151], v[172:175], v[56:59]
	v_mfma_f32_16x16x32_bf16 v[44:47], v[134:137], v[180:183], v[44:47]
	v_mfma_f32_16x16x32_bf16 v[40:43], v[148:151], v[180:183], v[40:43]
	v_mfma_f32_16x16x32_bf16 v[28:31], v[134:137], v[188:191], v[28:31]
	v_mfma_f32_16x16x32_bf16 v[24:27], v[148:151], v[188:191], v[24:27]
	v_mfma_f32_16x16x32_bf16 v[12:15], v[134:137], v[198:201], v[12:15]
	v_mfma_f32_16x16x32_bf16 v[8:11], v[148:151], v[198:201], v[8:11]
	v_mfma_f32_16x16x32_bf16 v[60:63], v[144:147], v[176:179], v[60:63]
	v_mfma_f32_16x16x32_bf16 v[56:59], v[152:155], v[176:179], v[56:59]
	v_mfma_f32_16x16x32_bf16 v[44:47], v[144:147], v[184:187], v[44:47]
	v_mfma_f32_16x16x32_bf16 v[40:43], v[152:155], v[184:187], v[40:43]
	v_mfma_f32_16x16x32_bf16 v[28:31], v[144:147], v[194:197], v[28:31]
	v_mfma_f32_16x16x32_bf16 v[24:27], v[152:155], v[194:197], v[24:27]
	v_mfma_f32_16x16x32_bf16 v[12:15], v[144:147], v[202:205], v[12:15]
	v_mfma_f32_16x16x32_bf16 v[8:11], v[152:155], v[202:205], v[8:11]
	s_setprio 0
	s_setprio 1
	v_mfma_f32_16x16x32_bf16 v[52:55], v[156:159], v[172:175], v[52:55]
	v_mfma_f32_16x16x32_bf16 v[48:51], v[164:167], v[172:175], v[48:51]
	v_mfma_f32_16x16x32_bf16 v[36:39], v[156:159], v[180:183], v[36:39]
	v_mfma_f32_16x16x32_bf16 v[32:35], v[164:167], v[180:183], v[32:35]
	v_mfma_f32_16x16x32_bf16 v[20:23], v[156:159], v[188:191], v[20:23]
	v_mfma_f32_16x16x32_bf16 v[16:19], v[164:167], v[188:191], v[16:19]
	v_mfma_f32_16x16x32_bf16 v[4:7], v[156:159], v[198:201], v[4:7]
	v_mfma_f32_16x16x32_bf16 v[0:3], v[164:167], v[198:201], v[0:3]
	v_mfma_f32_16x16x32_bf16 v[52:55], v[160:163], v[176:179], v[52:55]
	v_mfma_f32_16x16x32_bf16 v[48:51], v[168:171], v[176:179], v[48:51]
	v_mfma_f32_16x16x32_bf16 v[36:39], v[160:163], v[184:187], v[36:39]
	v_mfma_f32_16x16x32_bf16 v[32:35], v[168:171], v[184:187], v[32:35]
	v_mfma_f32_16x16x32_bf16 v[20:23], v[160:163], v[194:197], v[20:23]
	v_mfma_f32_16x16x32_bf16 v[16:19], v[168:171], v[194:197], v[16:19]
	v_mfma_f32_16x16x32_bf16 v[4:7], v[160:163], v[202:205], v[4:7]
	v_mfma_f32_16x16x32_bf16 v[0:3], v[168:171], v[202:205], v[0:3]
	s_setprio 0
	s_barrier
	s_add_i32 s57, s57, 2
	s_add_u32 s21, s21, 0x100
	s_addc_u32 s23, s23, 0
	s_cmp_gt_u32 s57, 13
	s_mov_b64 s[38:39], s[40:41]
	s_cbranch_scc0 .LBB0_2017
	v_mov_b32_e32 v134, v140
	v_mov_b32_e32 v135, v141
	s_lshl_b32 s8, s36, 8
	v_readlane_b32 s9, v253, 5
	s_add_i32 s8, s8, s9
	v_add_u32_e32 v134, s8, v134
	s_lshl_b32 s8, s56, 8
	v_readlane_b32 s9, v253, 19
	s_or_b32 s8, s8, s9
	v_lshl_add_u32 v136, v135, 3, s8
	v_ashrrev_i32_e32 v135, 12, v134
	v_mul_hi_i32_i24_e32 v139, 0x9000, v135
	v_mul_i32_i24_e32 v138, 0x9000, v135
	v_lshl_add_u64 v[138:139], s[12:13], 0, v[138:139]
	v_ashrrev_i32_e32 v137, 31, v136
	v_lshl_add_u64 v[138:139], v[136:137], 2, v[138:139]
	global_load_dwordx4 v[144:147], v[138:139], off
	global_load_dwordx4 v[148:151], v[138:139], off offset:16
	global_load_dwordx4 v[152:155], v[138:139], off offset:128
	global_load_dwordx4 v[156:159], v[138:139], off offset:144
	v_lshlrev_b32_e32 v135, 11, v134
	v_lshl_add_u32 v135, v136, 1, v135
	s_and_b64 vcc, exec, s[16:17]
	s_mov_b32 s36, s22
	s_mov_b32 s56, s20
	s_mov_b64 s[40:41], s[34:35]
	s_mov_b64 s[38:39], s[30:31]
	global_load_dwordx4 v[160:163], v135, s[26:27]
	global_load_dwordx4 v[164:167], v135, s[26:27] offset:64
	v_add_u32_e32 v202, 0x8000, v135
	global_load_dwordx4 v[168:171], v202, s[26:27]
	v_add_u32_e32 v202, 0x8000, v135
	global_load_dwordx4 v[172:175], v202, s[26:27] offset:64
	v_add_u32_e32 v202, 0x10000, v135
	global_load_dwordx4 v[176:179], v202, s[26:27]
	v_add_u32_e32 v202, 0x10000, v135
	global_load_dwordx4 v[180:183], v202, s[26:27] offset:64
	v_add_u32_e32 v202, 0x18000, v135
	global_load_dwordx4 v[184:187], v202, s[26:27]
	v_add_u32_e32 v202, 0x18000, v135
	global_load_dwordx4 v[188:191], v202, s[26:27] offset:64
	s_waitcnt vmcnt(7)
;     __device__ __forceinline__ void operator()(AccRef acc, int pm, int pn, int wr, int wc, int fr, int fq) const {
;     ...
;             for (int m = 0; m < 4; ++m) { const int row = EPI_ROW(ai, m); const float* gp = gate + (size_t)(row >> 12) * 9216; const size_t ro = (size_t)row * 1024;
; #pragma unroll
;                 for (int bj = 0; bj < 2; ++bj) { const int col = pn * 256 + wc * 64 + bj * 32 + 8 * fq;
;                     const f32x4 g0 = *(const f32x4*)(gp + col), g1 = *(const f32x4*)(gp + col + 4);
;                     f32x4 x0, x1;
;                     if (mode == 0) { x0 = *(const f32x4*)(xin_f + ro + col); x1 = *(const f32x4*)(xin_f + ro + col + 4); }
;                     else { const h16x8 h = *(const h16x8*)(xh + ro + col); x0 = (f32x4){(float)h[0], (float)h[1], (float)h[2], (float)h[3]}; x1 = (f32x4){(float)h[4], (float)h[5], (float)h[6], (float)h[7]}; }
;                     const f32x4 y0 = x0 + gs * g0 * acc[ai][bj][m][0], y1 = x1 + gs * g1 * acc[ai][bj][m][1];
;                     if (mode == 2) { *(f32x4*)(xout_f + ro + col) = y0; *(f32x4*)(xout_f + ro + col + 4) = y1; }
;                     else { h16x8 h; h[0] = (_Float16)y0[0]; h[1] = (_Float16)y0[1]; h[2] = (_Float16)y0[2]; h[3] = (_Float16)y0[3]; h[4] = (_Float16)y1[0]; h[5] = (_Float16)y1[1]; h[6] = (_Float16)y1[2]; h[7] = (_Float16)y1[3];
;                         *(h16x8*)(xh + ro + col) = h; } } }
	v_cvt_f32_f16_e32 v194, v160
	v_cvt_f32_f16_sdwa v195, v160 dst_sel:DWORD dst_unused:UNUSED_PAD src0_sel:WORD_1
	v_cvt_f32_f16_e32 v196, v161
	v_cvt_f32_f16_sdwa v197, v161 dst_sel:DWORD dst_unused:UNUSED_PAD src0_sel:WORD_1
	v_cvt_f32_f16_e32 v198, v162
	v_cvt_f32_f16_sdwa v199, v162 dst_sel:DWORD dst_unused:UNUSED_PAD src0_sel:WORD_1
	v_cvt_f32_f16_e32 v200, v163
	v_cvt_f32_f16_sdwa v201, v163 dst_sel:DWORD dst_unused:UNUSED_PAD src0_sel:WORD_1
	v_pk_fma_f32 v[126:127], v[126:127], v[146:147], v[196:197]
	v_pk_fma_f32 v[124:125], v[124:125], v[144:145], v[194:195]
	v_pk_fma_f32 v[122:123], v[122:123], v[150:151], v[200:201]
	v_pk_fma_f32 v[120:121], v[120:121], v[148:149], v[198:199]
	v_cvt_pk_f16_f32 v163, v122, v123
	v_cvt_pk_f16_f32 v162, v120, v121
	v_cvt_pk_f16_f32 v161, v126, v127
	v_cvt_pk_f16_f32 v160, v124, v125
	global_store_dwordx4 v135, v[160:163], s[26:27]
	s_nop 1
	v_add_u32_e32 v202, 0x40000, v135
	global_load_dwordx4 v[160:163], v202, s[26:27]
	s_waitcnt vmcnt(8)
	v_cvt_f32_f16_e32 v194, v164
	v_cvt_f32_f16_sdwa v195, v164 dst_sel:DWORD dst_unused:UNUSED_PAD src0_sel:WORD_1
	v_cvt_f32_f16_e32 v196, v165
	v_cvt_f32_f16_sdwa v197, v165 dst_sel:DWORD dst_unused:UNUSED_PAD src0_sel:WORD_1
	v_cvt_f32_f16_e32 v198, v166
	v_cvt_f32_f16_sdwa v199, v166 dst_sel:DWORD dst_unused:UNUSED_PAD src0_sel:WORD_1
	v_cvt_f32_f16_e32 v200, v167
	v_cvt_f32_f16_sdwa v201, v167 dst_sel:DWORD dst_unused:UNUSED_PAD src0_sel:WORD_1
	v_pk_fma_f32 v[118:119], v[118:119], v[154:155], v[196:197]
	v_pk_fma_f32 v[116:117], v[116:117], v[152:153], v[194:195]
	v_pk_fma_f32 v[114:115], v[114:115], v[158:159], v[200:201]
	v_pk_fma_f32 v[112:113], v[112:113], v[156:157], v[198:199]
	v_cvt_pk_f16_f32 v167, v114, v115
	v_cvt_pk_f16_f32 v166, v112, v113
	v_cvt_pk_f16_f32 v165, v118, v119
	v_cvt_pk_f16_f32 v164, v116, v117
	global_store_dwordx4 v135, v[164:167], s[26:27] offset:64
	s_nop 1
	v_add_u32_e32 v202, 0x40000, v135
	global_load_dwordx4 v[164:167], v202, s[26:27] offset:64
	s_waitcnt vmcnt(9)
	v_cvt_f32_f16_e32 v194, v168
	v_cvt_f32_f16_sdwa v195, v168 dst_sel:DWORD dst_unused:UNUSED_PAD src0_sel:WORD_1
	v_cvt_f32_f16_e32 v196, v169
	v_cvt_f32_f16_sdwa v197, v169 dst_sel:DWORD dst_unused:UNUSED_PAD src0_sel:WORD_1
	v_cvt_f32_f16_e32 v198, v170
	v_cvt_f32_f16_sdwa v199, v170 dst_sel:DWORD dst_unused:UNUSED_PAD src0_sel:WORD_1
	v_cvt_f32_f16_e32 v200, v171
	v_cvt_f32_f16_sdwa v201, v171 dst_sel:DWORD dst_unused:UNUSED_PAD src0_sel:WORD_1
	v_pk_fma_f32 v[110:111], v[110:111], v[146:147], v[196:197]
	v_pk_fma_f32 v[108:109], v[108:109], v[144:145], v[194:195]
	v_pk_fma_f32 v[106:107], v[106:107], v[150:151], v[200:201]
	v_pk_fma_f32 v[104:105], v[104:105], v[148:149], v[198:199]
	v_cvt_pk_f16_f32 v171, v106, v107
	v_cvt_pk_f16_f32 v170, v104, v105
	v_cvt_pk_f16_f32 v169, v110, v111
	v_cvt_pk_f16_f32 v168, v108, v109
	v_add_u32_e32 v203, 0x8000, v135
	global_store_dwordx4 v203, v[168:171], s[26:27]
	s_nop 1
	v_add_u32_e32 v202, 0x48000, v135
	global_load_dwordx4 v[168:171], v202, s[26:27]
	s_waitcnt vmcnt(10)
	v_cvt_f32_f16_e32 v194, v172
	v_cvt_f32_f16_sdwa v195, v172 dst_sel:DWORD dst_unused:UNUSED_PAD src0_sel:WORD_1
	v_cvt_f32_f16_e32 v196, v173
	v_cvt_f32_f16_sdwa v197, v173 dst_sel:DWORD dst_unused:UNUSED_PAD src0_sel:WORD_1
	v_cvt_f32_f16_e32 v198, v174
	v_cvt_f32_f16_sdwa v199, v174 dst_sel:DWORD dst_unused:UNUSED_PAD src0_sel:WORD_1
	v_cvt_f32_f16_e32 v200, v175
	v_cvt_f32_f16_sdwa v201, v175 dst_sel:DWORD dst_unused:UNUSED_PAD src0_sel:WORD_1
	v_pk_fma_f32 v[102:103], v[102:103], v[154:155], v[196:197]
	v_pk_fma_f32 v[100:101], v[100:101], v[152:153], v[194:195]
	v_pk_fma_f32 v[98:99], v[98:99], v[158:159], v[200:201]
	v_pk_fma_f32 v[96:97], v[96:97], v[156:157], v[198:199]
	v_cvt_pk_f16_f32 v175, v98, v99
	v_cvt_pk_f16_f32 v174, v96, v97
	v_cvt_pk_f16_f32 v173, v102, v103
	v_cvt_pk_f16_f32 v172, v100, v101
	v_add_u32_e32 v203, 0x8000, v135
	global_store_dwordx4 v203, v[172:175], s[26:27] offset:64
	s_nop 1
	v_add_u32_e32 v202, 0x48000, v135
	global_load_dwordx4 v[172:175], v202, s[26:27] offset:64
	s_waitcnt vmcnt(11)
	v_cvt_f32_f16_e32 v194, v176
	v_cvt_f32_f16_sdwa v195, v176 dst_sel:DWORD dst_unused:UNUSED_PAD src0_sel:WORD_1
	v_cvt_f32_f16_e32 v196, v177
	v_cvt_f32_f16_sdwa v197, v177 dst_sel:DWORD dst_unused:UNUSED_PAD src0_sel:WORD_1
	v_cvt_f32_f16_e32 v198, v178
	v_cvt_f32_f16_sdwa v199, v178 dst_sel:DWORD dst_unused:UNUSED_PAD src0_sel:WORD_1
	v_cvt_f32_f16_e32 v200, v179
	v_cvt_f32_f16_sdwa v201, v179 dst_sel:DWORD dst_unused:UNUSED_PAD src0_sel:WORD_1
	v_pk_fma_f32 v[94:95], v[94:95], v[146:147], v[196:197]
	v_pk_fma_f32 v[92:93], v[92:93], v[144:145], v[194:195]
	v_pk_fma_f32 v[90:91], v[90:91], v[150:151], v[200:201]
	v_pk_fma_f32 v[88:89], v[88:89], v[148:149], v[198:199]
	v_cvt_pk_f16_f32 v179, v90, v91
	v_cvt_pk_f16_f32 v178, v88, v89
	v_cvt_pk_f16_f32 v177, v94, v95
	v_cvt_pk_f16_f32 v176, v92, v93
	v_add_u32_e32 v203, 0x10000, v135
	global_store_dwordx4 v203, v[176:179], s[26:27]
	s_nop 1
	v_add_u32_e32 v202, 0x50000, v135
	global_load_dwordx4 v[176:179], v202, s[26:27]
	s_waitcnt vmcnt(12)
	v_cvt_f32_f16_e32 v194, v180
	v_cvt_f32_f16_sdwa v195, v180 dst_sel:DWORD dst_unused:UNUSED_PAD src0_sel:WORD_1
	v_cvt_f32_f16_e32 v196, v181
	v_cvt_f32_f16_sdwa v197, v181 dst_sel:DWORD dst_unused:UNUSED_PAD src0_sel:WORD_1
	v_cvt_f32_f16_e32 v198, v182
	v_cvt_f32_f16_sdwa v199, v182 dst_sel:DWORD dst_unused:UNUSED_PAD src0_sel:WORD_1
	v_cvt_f32_f16_e32 v200, v183
	v_cvt_f32_f16_sdwa v201, v183 dst_sel:DWORD dst_unused:UNUSED_PAD src0_sel:WORD_1
	v_pk_fma_f32 v[86:87], v[86:87], v[154:155], v[196:197]
	v_pk_fma_f32 v[84:85], v[84:85], v[152:153], v[194:195]
	v_pk_fma_f32 v[82:83], v[82:83], v[158:159], v[200:201]
	v_pk_fma_f32 v[80:81], v[80:81], v[156:157], v[198:199]
	v_cvt_pk_f16_f32 v183, v82, v83
	v_cvt_pk_f16_f32 v182, v80, v81
	v_cvt_pk_f16_f32 v181, v86, v87
	v_cvt_pk_f16_f32 v180, v84, v85
	v_add_u32_e32 v203, 0x10000, v135
	global_store_dwordx4 v203, v[180:183], s[26:27] offset:64
	s_nop 1
	v_add_u32_e32 v202, 0x50000, v135
	global_load_dwordx4 v[180:183], v202, s[26:27] offset:64
	s_waitcnt vmcnt(13)
;     __device__ __forceinline__ void operator()(AccRef acc, int pm, int pn, int wr, int wc, int fr, int fq) const {
;     ...
;             for (int m = 0; m < 4; ++m) { const int row = EPI_ROW(ai, m); const float* gp = gate + (size_t)(row >> 12) * 9216; const size_t ro = (size_t)row * 1024;
; #pragma unroll
;                 for (int bj = 0; bj < 2; ++bj) { const int col = pn * 256 + wc * 64 + bj * 32 + 8 * fq;
;                     const f32x4 g0 = *(const f32x4*)(gp + col), g1 = *(const f32x4*)(gp + col + 4);
;                     f32x4 x0, x1;
;                     if (mode == 0) { x0 = *(const f32x4*)(xin_f + ro + col); x1 = *(const f32x4*)(xin_f + ro + col + 4); }
;                     else { const h16x8 h = *(const h16x8*)(xh + ro + col); x0 = (f32x4){(float)h[0], (float)h[1], (float)h[2], (float)h[3]}; x1 = (f32x4){(float)h[4], (float)h[5], (float)h[6], (float)h[7]}; }
;                     const f32x4 y0 = x0 + gs * g0 * acc[ai][bj][m][0], y1 = x1 + gs * g1 * acc[ai][bj][m][1];
;                     if (mode == 2) { *(f32x4*)(xout_f + ro + col) = y0; *(f32x4*)(xout_f + ro + col + 4) = y1; }
;                     else { h16x8 h; h[0] = (_Float16)y0[0]; h[1] = (_Float16)y0[1]; h[2] = (_Float16)y0[2]; h[3] = (_Float16)y0[3]; h[4] = (_Float16)y1[0]; h[5] = (_Float16)y1[1]; h[6] = (_Float16)y1[2]; h[7] = (_Float16)y1[3];
;                         *(h16x8*)(xh + ro + col) = h; } } }
	v_cvt_f32_f16_e32 v194, v184
	v_cvt_f32_f16_sdwa v195, v184 dst_sel:DWORD dst_unused:UNUSED_PAD src0_sel:WORD_1
	v_cvt_f32_f16_e32 v196, v185
	v_cvt_f32_f16_sdwa v197, v185 dst_sel:DWORD dst_unused:UNUSED_PAD src0_sel:WORD_1
	v_cvt_f32_f16_e32 v198, v186
	v_cvt_f32_f16_sdwa v199, v186 dst_sel:DWORD dst_unused:UNUSED_PAD src0_sel:WORD_1
	v_cvt_f32_f16_e32 v200, v187
	v_cvt_f32_f16_sdwa v201, v187 dst_sel:DWORD dst_unused:UNUSED_PAD src0_sel:WORD_1
	v_pk_fma_f32 v[78:79], v[78:79], v[146:147], v[196:197]
	v_pk_fma_f32 v[76:77], v[76:77], v[144:145], v[194:195]
	v_pk_fma_f32 v[74:75], v[74:75], v[150:151], v[200:201]
	v_pk_fma_f32 v[72:73], v[72:73], v[148:149], v[198:199]
	v_cvt_pk_f16_f32 v187, v74, v75
	v_cvt_pk_f16_f32 v186, v72, v73
	v_cvt_pk_f16_f32 v185, v78, v79
	v_cvt_pk_f16_f32 v184, v76, v77
	v_add_u32_e32 v203, 0x18000, v135
	global_store_dwordx4 v203, v[184:187], s[26:27]
	s_nop 1
	v_add_u32_e32 v202, 0x58000, v135
	global_load_dwordx4 v[184:187], v202, s[26:27]
	s_waitcnt vmcnt(14)
	v_cvt_f32_f16_e32 v194, v188
	v_cvt_f32_f16_sdwa v195, v188 dst_sel:DWORD dst_unused:UNUSED_PAD src0_sel:WORD_1
	v_cvt_f32_f16_e32 v196, v189
	v_cvt_f32_f16_sdwa v197, v189 dst_sel:DWORD dst_unused:UNUSED_PAD src0_sel:WORD_1
	v_cvt_f32_f16_e32 v198, v190
	v_cvt_f32_f16_sdwa v199, v190 dst_sel:DWORD dst_unused:UNUSED_PAD src0_sel:WORD_1
	v_cvt_f32_f16_e32 v200, v191
	v_cvt_f32_f16_sdwa v201, v191 dst_sel:DWORD dst_unused:UNUSED_PAD src0_sel:WORD_1
	v_pk_fma_f32 v[70:71], v[70:71], v[154:155], v[196:197]
	v_pk_fma_f32 v[68:69], v[68:69], v[152:153], v[194:195]
	v_pk_fma_f32 v[66:67], v[66:67], v[158:159], v[200:201]
	v_pk_fma_f32 v[64:65], v[64:65], v[156:157], v[198:199]
	v_cvt_pk_f16_f32 v191, v66, v67
	v_cvt_pk_f16_f32 v190, v64, v65
	v_cvt_pk_f16_f32 v189, v70, v71
	v_cvt_pk_f16_f32 v188, v68, v69
	v_add_u32_e32 v203, 0x18000, v135
	global_store_dwordx4 v203, v[188:191], s[26:27] offset:64
	s_nop 1
	v_add_u32_e32 v202, 0x58000, v135
	global_load_dwordx4 v[188:191], v202, s[26:27] offset:64
	s_waitcnt vmcnt(14)
	v_cvt_f32_f16_e32 v194, v160
	v_cvt_f32_f16_sdwa v195, v160 dst_sel:DWORD dst_unused:UNUSED_PAD src0_sel:WORD_1
	v_cvt_f32_f16_e32 v196, v161
	v_cvt_f32_f16_sdwa v197, v161 dst_sel:DWORD dst_unused:UNUSED_PAD src0_sel:WORD_1
	v_cvt_f32_f16_e32 v198, v162
	v_cvt_f32_f16_sdwa v199, v162 dst_sel:DWORD dst_unused:UNUSED_PAD src0_sel:WORD_1
	v_cvt_f32_f16_e32 v200, v163
	v_cvt_f32_f16_sdwa v201, v163 dst_sel:DWORD dst_unused:UNUSED_PAD src0_sel:WORD_1
	v_pk_fma_f32 v[62:63], v[62:63], v[146:147], v[196:197]
	v_pk_fma_f32 v[60:61], v[60:61], v[144:145], v[194:195]
	v_pk_fma_f32 v[58:59], v[58:59], v[150:151], v[200:201]
	v_pk_fma_f32 v[56:57], v[56:57], v[148:149], v[198:199]
	v_cvt_pk_f16_f32 v163, v58, v59
	v_cvt_pk_f16_f32 v162, v56, v57
	v_cvt_pk_f16_f32 v161, v62, v63
	v_cvt_pk_f16_f32 v160, v60, v61
	v_add_u32_e32 v203, 0x40000, v135
	global_store_dwordx4 v203, v[160:163], s[26:27]
	s_waitcnt vmcnt(13)
	v_cvt_f32_f16_e32 v194, v164
	v_cvt_f32_f16_sdwa v195, v164 dst_sel:DWORD dst_unused:UNUSED_PAD src0_sel:WORD_1
	v_cvt_f32_f16_e32 v196, v165
	v_cvt_f32_f16_sdwa v197, v165 dst_sel:DWORD dst_unused:UNUSED_PAD src0_sel:WORD_1
	v_cvt_f32_f16_e32 v198, v166
	v_cvt_f32_f16_sdwa v199, v166 dst_sel:DWORD dst_unused:UNUSED_PAD src0_sel:WORD_1
	v_cvt_f32_f16_e32 v200, v167
	v_cvt_f32_f16_sdwa v201, v167 dst_sel:DWORD dst_unused:UNUSED_PAD src0_sel:WORD_1
	v_pk_fma_f32 v[54:55], v[54:55], v[154:155], v[196:197]
	v_pk_fma_f32 v[52:53], v[52:53], v[152:153], v[194:195]
	v_pk_fma_f32 v[50:51], v[50:51], v[158:159], v[200:201]
	v_pk_fma_f32 v[48:49], v[48:49], v[156:157], v[198:199]
	v_cvt_pk_f16_f32 v167, v50, v51
	v_cvt_pk_f16_f32 v166, v48, v49
	v_cvt_pk_f16_f32 v165, v54, v55
	v_cvt_pk_f16_f32 v164, v52, v53
	v_add_u32_e32 v203, 0x40000, v135
	global_store_dwordx4 v203, v[164:167], s[26:27] offset:64
	s_waitcnt vmcnt(12)
	v_cvt_f32_f16_e32 v194, v168
	v_cvt_f32_f16_sdwa v195, v168 dst_sel:DWORD dst_unused:UNUSED_PAD src0_sel:WORD_1
	v_cvt_f32_f16_e32 v196, v169
	v_cvt_f32_f16_sdwa v197, v169 dst_sel:DWORD dst_unused:UNUSED_PAD src0_sel:WORD_1
	v_cvt_f32_f16_e32 v198, v170
	v_cvt_f32_f16_sdwa v199, v170 dst_sel:DWORD dst_unused:UNUSED_PAD src0_sel:WORD_1
	v_cvt_f32_f16_e32 v200, v171
	v_cvt_f32_f16_sdwa v201, v171 dst_sel:DWORD dst_unused:UNUSED_PAD src0_sel:WORD_1
	v_pk_fma_f32 v[46:47], v[46:47], v[146:147], v[196:197]
	v_pk_fma_f32 v[44:45], v[44:45], v[144:145], v[194:195]
	v_pk_fma_f32 v[42:43], v[42:43], v[150:151], v[200:201]
	v_pk_fma_f32 v[40:41], v[40:41], v[148:149], v[198:199]
	v_cvt_pk_f16_f32 v171, v42, v43
	v_cvt_pk_f16_f32 v170, v40, v41
	v_cvt_pk_f16_f32 v169, v46, v47
	v_cvt_pk_f16_f32 v168, v44, v45
	v_add_u32_e32 v203, 0x48000, v135
	global_store_dwordx4 v203, v[168:171], s[26:27]
	s_waitcnt vmcnt(11)
;     __device__ __forceinline__ void operator()(AccRef acc, int pm, int pn, int wr, int wc, int fr, int fq) const {
;     ...
;             for (int m = 0; m < 4; ++m) { const int row = EPI_ROW(ai, m); const float* gp = gate + (size_t)(row >> 12) * 9216; const size_t ro = (size_t)row * 1024;
; #pragma unroll
;                 for (int bj = 0; bj < 2; ++bj) { const int col = pn * 256 + wc * 64 + bj * 32 + 8 * fq;
;                     const f32x4 g0 = *(const f32x4*)(gp + col), g1 = *(const f32x4*)(gp + col + 4);
;                     f32x4 x0, x1;
;                     if (mode == 0) { x0 = *(const f32x4*)(xin_f + ro + col); x1 = *(const f32x4*)(xin_f + ro + col + 4); }
;                     else { const h16x8 h = *(const h16x8*)(xh + ro + col); x0 = (f32x4){(float)h[0], (float)h[1], (float)h[2], (float)h[3]}; x1 = (f32x4){(float)h[4], (float)h[5], (float)h[6], (float)h[7]}; }
;                     const f32x4 y0 = x0 + gs * g0 * acc[ai][bj][m][0], y1 = x1 + gs * g1 * acc[ai][bj][m][1];
;                     if (mode == 2) { *(f32x4*)(xout_f + ro + col) = y0; *(f32x4*)(xout_f + ro + col + 4) = y1; }
;                     else { h16x8 h; h[0] = (_Float16)y0[0]; h[1] = (_Float16)y0[1]; h[2] = (_Float16)y0[2]; h[3] = (_Float16)y0[3]; h[4] = (_Float16)y1[0]; h[5] = (_Float16)y1[1]; h[6] = (_Float16)y1[2]; h[7] = (_Float16)y1[3];
;                         *(h16x8*)(xh + ro + col) = h; } } }
	v_cvt_f32_f16_e32 v194, v172
	v_cvt_f32_f16_sdwa v195, v172 dst_sel:DWORD dst_unused:UNUSED_PAD src0_sel:WORD_1
	v_cvt_f32_f16_e32 v196, v173
	v_cvt_f32_f16_sdwa v197, v173 dst_sel:DWORD dst_unused:UNUSED_PAD src0_sel:WORD_1
	v_cvt_f32_f16_e32 v198, v174
	v_cvt_f32_f16_sdwa v199, v174 dst_sel:DWORD dst_unused:UNUSED_PAD src0_sel:WORD_1
	v_cvt_f32_f16_e32 v200, v175
	v_cvt_f32_f16_sdwa v201, v175 dst_sel:DWORD dst_unused:UNUSED_PAD src0_sel:WORD_1
	v_pk_fma_f32 v[38:39], v[38:39], v[154:155], v[196:197]
	v_pk_fma_f32 v[36:37], v[36:37], v[152:153], v[194:195]
	v_pk_fma_f32 v[34:35], v[34:35], v[158:159], v[200:201]
	v_pk_fma_f32 v[32:33], v[32:33], v[156:157], v[198:199]
	v_cvt_pk_f16_f32 v175, v34, v35
	v_cvt_pk_f16_f32 v174, v32, v33
	v_cvt_pk_f16_f32 v173, v38, v39
	v_cvt_pk_f16_f32 v172, v36, v37
	v_add_u32_e32 v203, 0x48000, v135
	global_store_dwordx4 v203, v[172:175], s[26:27] offset:64
	s_waitcnt vmcnt(10)
	v_cvt_f32_f16_e32 v194, v176
	v_cvt_f32_f16_sdwa v195, v176 dst_sel:DWORD dst_unused:UNUSED_PAD src0_sel:WORD_1
	v_cvt_f32_f16_e32 v196, v177
	v_cvt_f32_f16_sdwa v197, v177 dst_sel:DWORD dst_unused:UNUSED_PAD src0_sel:WORD_1
	v_cvt_f32_f16_e32 v198, v178
	v_cvt_f32_f16_sdwa v199, v178 dst_sel:DWORD dst_unused:UNUSED_PAD src0_sel:WORD_1
	v_cvt_f32_f16_e32 v200, v179
	v_cvt_f32_f16_sdwa v201, v179 dst_sel:DWORD dst_unused:UNUSED_PAD src0_sel:WORD_1
	v_pk_fma_f32 v[30:31], v[30:31], v[146:147], v[196:197]
	v_pk_fma_f32 v[28:29], v[28:29], v[144:145], v[194:195]
	v_pk_fma_f32 v[26:27], v[26:27], v[150:151], v[200:201]
	v_pk_fma_f32 v[24:25], v[24:25], v[148:149], v[198:199]
	v_cvt_pk_f16_f32 v179, v26, v27
	v_cvt_pk_f16_f32 v178, v24, v25
	v_cvt_pk_f16_f32 v177, v30, v31
	v_cvt_pk_f16_f32 v176, v28, v29
	v_add_u32_e32 v203, 0x50000, v135
	global_store_dwordx4 v203, v[176:179], s[26:27]
	s_waitcnt vmcnt(9)
	v_cvt_f32_f16_e32 v194, v180
	v_cvt_f32_f16_sdwa v195, v180 dst_sel:DWORD dst_unused:UNUSED_PAD src0_sel:WORD_1
	v_cvt_f32_f16_e32 v196, v181
	v_cvt_f32_f16_sdwa v197, v181 dst_sel:DWORD dst_unused:UNUSED_PAD src0_sel:WORD_1
	v_cvt_f32_f16_e32 v198, v182
	v_cvt_f32_f16_sdwa v199, v182 dst_sel:DWORD dst_unused:UNUSED_PAD src0_sel:WORD_1
	v_cvt_f32_f16_e32 v200, v183
	v_cvt_f32_f16_sdwa v201, v183 dst_sel:DWORD dst_unused:UNUSED_PAD src0_sel:WORD_1
	v_pk_fma_f32 v[22:23], v[22:23], v[154:155], v[196:197]
	v_pk_fma_f32 v[20:21], v[20:21], v[152:153], v[194:195]
	v_pk_fma_f32 v[18:19], v[18:19], v[158:159], v[200:201]
	v_pk_fma_f32 v[16:17], v[16:17], v[156:157], v[198:199]
	v_cvt_pk_f16_f32 v183, v18, v19
	v_cvt_pk_f16_f32 v182, v16, v17
	v_cvt_pk_f16_f32 v181, v22, v23
	v_cvt_pk_f16_f32 v180, v20, v21
	v_add_u32_e32 v203, 0x50000, v135
	global_store_dwordx4 v203, v[180:183], s[26:27] offset:64
	s_waitcnt vmcnt(8)
	v_cvt_f32_f16_e32 v194, v184
	v_cvt_f32_f16_sdwa v195, v184 dst_sel:DWORD dst_unused:UNUSED_PAD src0_sel:WORD_1
	v_cvt_f32_f16_e32 v196, v185
	v_cvt_f32_f16_sdwa v197, v185 dst_sel:DWORD dst_unused:UNUSED_PAD src0_sel:WORD_1
	v_cvt_f32_f16_e32 v198, v186
	v_cvt_f32_f16_sdwa v199, v186 dst_sel:DWORD dst_unused:UNUSED_PAD src0_sel:WORD_1
	v_cvt_f32_f16_e32 v200, v187
	v_cvt_f32_f16_sdwa v201, v187 dst_sel:DWORD dst_unused:UNUSED_PAD src0_sel:WORD_1
	v_pk_fma_f32 v[14:15], v[14:15], v[146:147], v[196:197]
	v_pk_fma_f32 v[12:13], v[12:13], v[144:145], v[194:195]
	v_pk_fma_f32 v[10:11], v[10:11], v[150:151], v[200:201]
	v_pk_fma_f32 v[8:9], v[8:9], v[148:149], v[198:199]
	v_cvt_pk_f16_f32 v187, v10, v11
	v_cvt_pk_f16_f32 v186, v8, v9
	v_cvt_pk_f16_f32 v185, v14, v15
	v_cvt_pk_f16_f32 v184, v12, v13
	v_add_u32_e32 v203, 0x58000, v135
	global_store_dwordx4 v203, v[184:187], s[26:27]
	s_waitcnt vmcnt(7)
	v_cvt_f32_f16_e32 v194, v188
	v_cvt_f32_f16_sdwa v195, v188 dst_sel:DWORD dst_unused:UNUSED_PAD src0_sel:WORD_1
	v_cvt_f32_f16_e32 v196, v189
	v_cvt_f32_f16_sdwa v197, v189 dst_sel:DWORD dst_unused:UNUSED_PAD src0_sel:WORD_1
	v_cvt_f32_f16_e32 v198, v190
	v_cvt_f32_f16_sdwa v199, v190 dst_sel:DWORD dst_unused:UNUSED_PAD src0_sel:WORD_1
	v_cvt_f32_f16_e32 v200, v191
	v_cvt_f32_f16_sdwa v201, v191 dst_sel:DWORD dst_unused:UNUSED_PAD src0_sel:WORD_1
	v_pk_fma_f32 v[6:7], v[6:7], v[154:155], v[196:197]
	v_pk_fma_f32 v[4:5], v[4:5], v[152:153], v[194:195]
	v_pk_fma_f32 v[2:3], v[2:3], v[158:159], v[200:201]
	v_pk_fma_f32 v[0:1], v[0:1], v[156:157], v[198:199]
	v_cvt_pk_f16_f32 v191, v2, v3
	v_cvt_pk_f16_f32 v190, v0, v1
	v_cvt_pk_f16_f32 v189, v6, v7
	v_cvt_pk_f16_f32 v188, v4, v5
	v_add_u32_e32 v203, 0x58000, v135
	global_store_dwordx4 v203, v[188:191], s[26:27] offset:64
	s_cbranch_vccz .LBB0_2010
	v_readlane_b32 s8, v253, 10
	s_waitcnt vmcnt(0)
	v_readlane_b32 s9, v253, 11
	s_andn2_b64 vcc, exec, s[8:9]
	s_cbranch_vccnz .LBB0_2021
	s_barrier
